# v54 + P9 body: bu via v_mfma_f32_4x4x4_16b_bf16 (A=U broadcast, cbsz:4/abid) straight into f32 lane-per-state registers; no bu LDS round trip, scalar-FMA recurrence
# speedup vs baseline: 1.0172x; 1.0132x over previous
; #define LAS __attribute__((address_space(3)))
; __device__ __forceinline__ void s5_out_phase(LAS unsigned char* lds, const bf16_t* UZ, const unsigned char* ws, const float* dskip, bf16_t* YG) {
;     const int lane = threadIdx.x & 63, wave = __builtin_amdgcn_readfirstlane(threadIdx.x >> 6);
;     LAS unsigned char* wl = lds + wave * S5_WAVE_LDS;
;     const int gw = blockIdx.x * 8 + wave, NGW = gridDim.x * 8;
;     const float* E = (const float*)(ws + WS_E);
;     const int g = gw & 63, fr = lane & 15, fq = lane >> 4;
;     const f32x4 dsk = *(const f32x4*)(dskip + 16 * g + 4 * fq);
;     bf16x4 Bf[2][8]; bf16x8 Cf[2][4]; f32x4 ap[2];
; #pragma unroll
;     for (int dir = 0; dir < 2; ++dir) {
;         const int pair = dir * 64 + g;
;         const bf16_t* Bb = (const bf16_t*)(ws + WS_BB) + (size_t)pair * 128 * 16;
;         const bf16_t* Cm = (const bf16_t*)(ws + WS_CM) + (size_t)pair * 16 * 128;
; #pragma unroll
;         for (int nt = 0; nt < 8; ++nt) Bf[dir][nt] = *(const bf16x4*)(Bb + (16 * nt + fr) * 16 + 4 * fq);
; #pragma unroll
;         for (int ks = 0; ks < 4; ++ks) Cf[dir][ks] = *(const bf16x8*)(Cm + fr * 128 + 8 * fq + 32 * ks);
;         ap[dir] = ((const f32x4*)(ws + WS_APOW))[pair * 64 + lane];
;     }
;     const int wofs = (fr >> 1) * 80 + (fr & 1) * 32 + 8 * fq;
;     const int sstep = NGW >> 6;
;     const float* QE = (const float*)(ws + WS_QE);
;     bf16x4 Un[4]; f32x2 rp[2], rq[2][3];
;     ...
;     { const int slot = gw >> 6, b = slot >> 6, tt = slot & 63;
;       load_uf(Un, UZ, b * SEQ + 64 * tt, g, lane);
;       S5_LOADRAW(b, tt); }
.LBB0_752:
	s_cmp_lt_i32 s68, 10
	s_cselect_b64 s[0:1], -1, 0
	s_cmp_gt_i32 s69, 9
	s_cselect_b64 s[2:3], -1, 0
	s_and_b64 s[0:1], s[0:1], s[2:3]
	s_andn2_b64 vcc, exec, s[0:1]
	s_cbranch_vccnz .LBB0_762
	v_readfirstlane_b32 s2, v192
	s_lshr_b32 s8, s2, 6
	s_lshl_b32 s2, s12, 3
	s_add_i32 s24, s8, s2
	s_ashr_i32 s5, s24, 6
	s_cmpk_gt_i32 s5, 0xff
	s_cbranch_scc1 .LBB0_762
	s_waitcnt vmcnt(0)
	v_lshrrev_b32_e32 v0, 1, v192
	v_and_b32_e32 v46, 24, v0
	v_mov_b32_e32 v47, 0
	v_and_b32_e32 v182, 15, v192
	v_lshl_add_u64 v[0:1], s[30:31], 0, v[46:47]
	s_mov_b64 s[22:23], 0x100000
	v_lshl_add_u64 v[16:17], v[0:1], 0, s[22:23]
	v_lshlrev_b32_e32 v0, 8, v182
	v_mov_b32_e32 v1, v47
	v_lshl_add_u64 v[0:1], s[30:31], 0, v[0:1]
	v_and_b32_e32 v44, 48, v192
	v_mov_b32_e32 v45, v47
	s_lshl_b32 s4, s14, 3
	s_and_b32 s9, s24, 63
	v_lshl_add_u64 v[0:1], v[0:1], 0, v[44:45]
	s_mov_b64 s[22:23], 0x180000
	v_lshl_add_u64 v[20:21], v[0:1], 0, s[22:23]
	s_add_u32 s22, s30, 0x80000
	s_mov_b32 s3, 0
	s_addc_u32 s23, s31, 0
	s_lshl_b32 s2, s9, 12
	v_lshl_add_u64 v[0:1], v[16:17], 0, s[2:3]
	v_lshlrev_b32_e32 v18, 5, v182
	v_mov_b32_e32 v19, v47
	s_or_b32 s36, s9, 64
	v_and_b32_e32 v56, 63, v192
	v_lshl_add_u64 v[0:1], v[0:1], 0, v[18:19]
	v_lshl_add_u64 v[22:23], v[20:21], 0, s[2:3]
	s_lshl_b32 s25, s9, 6
	s_lshl_b32 s2, s36, 12
	v_and_b32_e32 v236, 63, v192
	v_lshlrev_b32_e32 v236, 6, v236
	v_mov_b32_e32 v237, 0
	s_add_u32 s98, s30, 0x100000
	s_addc_u32 s99, s31, 0
	s_lshl_b32 s100, s9, 12
	s_add_u32 s98, s98, s100
	s_addc_u32 s99, s99, 0
	v_lshl_add_u64 v[234:235], s[98:99], 0, v[236:237]
	s_add_u32 s98, s98, 0x40000
	s_addc_u32 s99, s99, 0
	v_lshl_add_u64 v[238:239], s[98:99], 0, v[236:237]
	global_load_dwordx2 v[60:61], v[234:235], off
	global_load_dwordx2 v[62:63], v[234:235], off offset:8
	global_load_dwordx2 v[64:65], v[234:235], off offset:16
	global_load_dwordx2 v[66:67], v[234:235], off offset:24
	global_load_dwordx2 v[68:69], v[234:235], off offset:32
	global_load_dwordx2 v[70:71], v[234:235], off offset:40
	global_load_dwordx2 v[72:73], v[234:235], off offset:48
	global_load_dwordx2 v[74:75], v[234:235], off offset:56
	s_nop 0
	global_load_dwordx4 v[0:3], v[22:23], off
	global_load_dwordx4 v[4:7], v[22:23], off offset:64
	global_load_dwordx4 v[8:11], v[22:23], off offset:128
	global_load_dwordx4 v[12:15], v[22:23], off offset:192
	v_or_b32_e32 v22, s25, v56
	v_lshl_add_u64 v[16:17], v[16:17], 0, s[2:3]
	v_lshlrev_b32_e32 v24, 4, v22
	v_lshl_add_u64 v[22:23], v[16:17], 0, v[18:19]
	v_lshl_add_u64 v[36:37], v[20:21], 0, s[2:3]
	global_load_dwordx4 v[16:19], v24, s[22:23]
	global_load_dwordx2 v[76:77], v[238:239], off
	global_load_dwordx2 v[78:79], v[238:239], off offset:8
	global_load_dwordx2 v[80:81], v[238:239], off offset:16
	global_load_dwordx2 v[82:83], v[238:239], off offset:24
	global_load_dwordx2 v[84:85], v[238:239], off offset:32
	global_load_dwordx2 v[86:87], v[238:239], off offset:40
	global_load_dwordx2 v[88:89], v[238:239], off offset:48
	global_load_dwordx2 v[90:91], v[238:239], off offset:56
	s_nop 0
	global_load_dwordx4 v[20:23], v[36:37], off
	global_load_dwordx4 v[24:27], v[36:37], off offset:64
	global_load_dwordx4 v[28:31], v[36:37], off offset:128
	global_load_dwordx4 v[32:35], v[36:37], off offset:192
	v_lshlrev_b32_e32 v36, 4, v56
	v_lshl_or_b32 v36, s36, 10, v36
	s_add_u32 s2, s30, 0xc200000
	global_load_dwordx4 v[36:39], v36, s[22:23]
	s_addc_u32 s3, s31, 0
	s_lshl_b32 s22, s9, 5
	s_add_u32 s36, s18, s22
	s_addc_u32 s37, s19, 0
	v_lshlrev_b32_e32 v48, 2, v56
	v_mov_b32_e32 v49, v47
	v_lshl_add_u64 v[92:93], s[36:37], 0, v[46:47]
	v_lshl_add_u64 v[40:41], s[30:31], 0, v[48:49]
	s_mov_b64 s[36:37], 0x1700000
	v_lshl_add_u64 v[94:95], v[40:41], 0, s[36:37]
	s_ashr_i32 s36, s24, 5
	s_and_b32 s36, s36, 0xffffff80
	s_or_b32 s40, s9, s36
	s_mulk_i32 s8, 0x4a00
	s_or_b32 s38, s40, 64
	s_bfe_i32 s23, s14, 0x1a0003
	s_add_i32 s8, s8, 0
	s_mul_i32 s36, s38, 0x600
	s_mul_hi_i32 s37, s38, 0x600
	s_add_u32 s36, s2, s36
	s_addc_u32 s37, s3, s37
	s_bfe_u32 s42, s24, 0x60006
	s_mul_hi_i32 s39, s38, 0x44
	s_mulk_i32 s38, 0x44
	s_sub_i32 s41, 0x43, s42
	s_add_u32 s38, s38, s41
	s_addc_u32 s39, s39, 0
	s_lshl_b64 s[38:39], s[38:39], 9
	v_lshl_add_u64 v[40:41], v[94:95], 0, s[38:39]
	s_mul_i32 s38, s40, 0x600
	s_mul_hi_i32 s39, s40, 0x600
	s_add_u32 s38, s2, s38
	s_addc_u32 s39, s3, s39
	s_mul_hi_i32 s41, s40, 0x44
	s_mulk_i32 s40, 0x44
	s_add_i32 s43, s42, 4
	s_add_u32 s40, s40, s43
	s_addc_u32 s41, s41, 0
	s_lshl_b64 s[40:41], s[40:41], 9
	v_lshl_add_u64 v[42:43], v[94:95], 0, s[40:41]
	s_lshl_b32 s40, s42, 6
	s_and_b32 s24, s24, 0xfffff000
	s_or_b32 s24, s40, s24
	global_load_dword v183, v48, s[38:39] offset:1024
	global_load_dword v184, v48, s[38:39] offset:1280
	global_load_dword v96, v48, s[38:39] offset:512
	global_load_dword v97, v48, s[38:39] offset:768
	global_load_dword v99, v48, s[38:39] offset:256
	global_load_dword v106, v[40:41], off
	global_load_dword v107, v[40:41], off offset:256
	global_load_dword v100, v[42:43], off
	v_or_b32_e32 v40, s24, v182
	v_or_b32_e32 v50, 48, v40
	v_or_b32_e32 v52, 32, v40
	v_or_b32_e32 v54, 16, v40
	v_ashrrev_i32_e32 v51, 31, v50
	v_ashrrev_i32_e32 v53, 31, v52
	v_ashrrev_i32_e32 v55, 31, v54
	v_ashrrev_i32_e32 v41, 31, v40
	v_lshlrev_b64 v[50:51], 12, v[50:51]
	v_lshlrev_b64 v[52:53], 12, v[52:53]
	v_lshlrev_b64 v[54:55], 12, v[54:55]
	v_lshlrev_b64 v[40:41], 12, v[40:41]
	v_lshl_add_u64 v[50:51], v[92:93], 0, v[50:51]
	v_lshl_add_u64 v[52:53], v[92:93], 0, v[52:53]
	v_lshl_add_u64 v[54:55], v[92:93], 0, v[54:55]
	global_load_dword v101, v[42:43], off offset:256
	global_load_dwordx2 v[116:117], v[50:51], off
	global_load_dwordx2 v[168:169], v[52:53], off
	global_load_dwordx2 v[170:171], v[54:55], off
	v_lshl_add_u64 v[40:41], v[92:93], 0, v[40:41]
	global_load_dword v185, v48, s[36:37] offset:1024
	global_load_dword v186, v48, s[36:37] offset:1280
	global_load_dword v140, v48, s[36:37] offset:512
	global_load_dword v98, v48, s[38:39]
	global_load_dword v141, v48, s[36:37] offset:768
	global_load_dword v144, v48, s[36:37]
	global_load_dword v145, v48, s[36:37] offset:256
	global_load_dwordx2 v[172:173], v[40:41], off
	v_bfe_u32 v40, v192, 1, 3
	v_lshlrev_b32_e32 v41, 5, v192
	s_add_u32 s20, s20, s25
	v_mul_u32_u24_e32 v40, 0x50, v40
	v_and_b32_e32 v41, 32, v41
	s_addc_u32 s21, s21, 0
	v_add3_u32 v45, v40, v41, v46
	global_load_dwordx4 v[40:43], v44, s[20:21]
	s_waitcnt vmcnt(34)
; __device__ __forceinline__ f32x2 s5_carry(const f32x2 pre, const f32x2 (&qe)[3], const f32x4 ap, int c) {
;     const int q = c / 17, k = c - 17 * q;
;     if (q == 0) return pre;
;     float A1r = ap.z, A1i = ap.w;
;     float A2r = A1r, A2i = A1i; cmul(A2r, A2i, A1r, A1i);
;     float A4r = A2r, A4i = A2i; cmul(A4r, A4i, A2r, A2i);
;     float A8r = A4r, A8i = A4i; cmul(A8r, A8i, A4r, A4i);
;     float A16r = A8r, A16i = A8i; cmul(A16r, A16i, A8r, A8i);
;     float A17r = A16r, A17i = A16i; cmul(A17r, A17i, A1r, A1i);
;     float sr = qe[0].x, si = qe[0].y;
;     if (q >= 2) { cmul(sr, si, A17r, A17i); sr += qe[1].x; si += qe[1].y; }
;     if (q >= 3) { cmul(sr, si, A17r, A17i); sr += qe[2].x; si += qe[2].y; }
; __device__ __forceinline__ void s5_out_phase(LAS unsigned char* lds, const bf16_t* UZ, const unsigned char* ws, const float* dskip, bf16_t* YG) {
;     ...
;     const int wofs = (fr >> 1) * 80 + (fr & 1) * 32 + 8 * fq;
;     const int sstep = NGW >> 6;
;     const float* QE = (const float*)(ws + WS_QE);
	v_mov_b32_e32 v50, v19
	v_pk_mul_f32 v[50:51], v[50:51], v[18:19] op_sel_hi:[0,1]
	v_pk_fma_f32 v[102:103], v[18:19], v[18:19], v[50:51] op_sel:[0,1,0] op_sel_hi:[0,0,1]
	v_pk_fma_f32 v[104:105], v[18:19], v[18:19], v[50:51] op_sel:[0,1,0] op_sel_hi:[0,0,1] neg_lo:[0,0,1] neg_hi:[0,0,1]
	v_pk_mov_b32 v[52:53], v[104:105], v[102:103] op_sel:[1,0]
	v_mov_b32_e32 v50, v102
	v_mov_b32_e32 v51, v105
	v_pk_mul_f32 v[52:53], v[102:103], v[52:53] op_sel_hi:[0,1]
	v_pk_fma_f32 v[108:109], v[50:51], v[104:105], v[52:53] op_sel:[0,1,0]
	v_pk_fma_f32 v[110:111], v[50:51], v[104:105], v[52:53] op_sel:[0,1,0] neg_lo:[0,0,1] neg_hi:[0,0,1]
	v_mov_b32_e32 v50, v108
	v_pk_mov_b32 v[52:53], v[110:111], v[108:109] op_sel:[1,0]
	v_mov_b32_e32 v51, v111
	v_pk_mul_f32 v[52:53], v[108:109], v[52:53] op_sel_hi:[0,1]
	v_pk_fma_f32 v[112:113], v[50:51], v[110:111], v[52:53] op_sel:[0,1,0]
	v_pk_fma_f32 v[114:115], v[50:51], v[110:111], v[52:53] op_sel:[0,1,0] neg_lo:[0,0,1] neg_hi:[0,0,1]
	s_waitcnt vmcnt(21)
	v_mov_b32_e32 v52, v39
	v_pk_mul_f32 v[52:53], v[52:53], v[38:39] op_sel_hi:[0,1]
	v_pk_fma_f32 v[126:127], v[38:39], v[38:39], v[52:53] op_sel:[0,1,0] op_sel_hi:[0,0,1]
	v_pk_fma_f32 v[128:129], v[38:39], v[38:39], v[52:53] op_sel:[0,1,0] op_sel_hi:[0,0,1] neg_lo:[0,0,1] neg_hi:[0,0,1]
	v_pk_mov_b32 v[54:55], v[128:129], v[126:127] op_sel:[1,0]
	v_mov_b32_e32 v52, v126
	v_mov_b32_e32 v53, v129
	v_pk_mul_f32 v[54:55], v[126:127], v[54:55] op_sel_hi:[0,1]
	v_pk_fma_f32 v[130:131], v[52:53], v[128:129], v[54:55] op_sel:[0,1,0]
	v_pk_fma_f32 v[132:133], v[52:53], v[128:129], v[54:55] op_sel:[0,1,0] neg_lo:[0,0,1] neg_hi:[0,0,1]
	v_mov_b32_e32 v52, v130
	v_pk_mov_b32 v[54:55], v[132:133], v[130:131] op_sel:[1,0]
	v_mov_b32_e32 v53, v133
	v_pk_mul_f32 v[54:55], v[130:131], v[54:55] op_sel_hi:[0,1]
	v_pk_fma_f32 v[134:135], v[52:53], v[132:133], v[54:55] op_sel:[0,1,0]
	v_pk_fma_f32 v[136:137], v[52:53], v[132:133], v[54:55] op_sel:[0,1,0] neg_lo:[0,0,1] neg_hi:[0,0,1]
	v_mov_b32_e32 v113, v115
	v_mul_f32_e32 v50, v115, v115
	v_mov_b32_e32 v135, v137
	v_mul_f32_e32 v52, v137, v137
	v_pk_fma_f32 v[118:119], v[112:113], v[112:113], v[50:51] op_sel_hi:[1,1,0] neg_lo:[1,0,0] neg_hi:[1,0,0]
	v_pk_mul_f32 v[50:51], v[112:113], v[114:115] op_sel:[0,1] op_sel_hi:[1,0]
	v_pk_fma_f32 v[138:139], v[134:135], v[134:135], v[52:53] op_sel_hi:[1,1,0] neg_lo:[1,0,0] neg_hi:[1,0,0]
	v_pk_mul_f32 v[52:53], v[134:135], v[136:137] op_sel:[0,1] op_sel_hi:[1,0]
	v_pk_add_f32 v[120:121], v[50:51], v[50:51]
	v_pk_add_f32 v[142:143], v[52:53], v[52:53]
	s_movk_i32 s20, 0x110
	v_mov_b32_e32 v55, s8
	v_pk_mul_f32 v[50:51], v[18:19], v[120:121] op_sel_hi:[1,0]
	v_pk_mul_f32 v[52:53], v[38:39], v[142:143] op_sel_hi:[1,0]
	v_mad_u32_u24 v55, v182, s20, v55
	s_add_u32 s20, s6, s22
	v_pk_fma_f32 v[122:123], v[18:19], v[118:119], v[50:51] op_sel:[1,0,0] op_sel_hi:[0,0,1]
	v_pk_fma_f32 v[50:51], v[18:19], v[118:119], v[50:51] op_sel:[1,0,0] op_sel_hi:[0,0,1] neg_lo:[0,0,1] neg_hi:[0,0,1]
	v_pk_fma_f32 v[146:147], v[38:39], v[138:139], v[52:53] op_sel:[1,0,0] op_sel_hi:[0,0,1]
	v_pk_fma_f32 v[52:53], v[38:39], v[138:139], v[52:53] op_sel:[1,0,0] op_sel_hi:[0,0,1] neg_lo:[0,0,1] neg_hi:[0,0,1]
	v_mul_u32_u24_e32 v54, 0x50, v56
	s_addc_u32 s21, s7, 0
	v_mov_b32_e32 v124, v122
	v_mov_b32_e32 v125, v51
	v_mov_b32_e32 v148, v146
	v_mov_b32_e32 v149, v53
	v_mov_b32_e32 v150, v16
	v_mov_b32_e32 v151, v16
	v_xor_b32_e32 v16, 0x80000000, v17
	v_add_u32_e32 v103, s8, v48
	v_mov_b32_e32 v152, v36
	v_mov_b32_e32 v153, v36
	v_xor_b32_e32 v36, 0x80000000, v37
	v_lshl_add_u64 v[154:155], s[20:21], 0, v[46:47]
	v_mov_b32_e32 v156, v53
	v_mov_b32_e32 v157, v53
	v_pk_mov_b32 v[158:159], v[52:53], v[146:147] op_sel:[1,0]
	v_mov_b32_e32 v160, v51
	v_mov_b32_e32 v161, v51
	v_pk_mov_b32 v[162:163], v[50:51], v[122:123] op_sel:[1,0]
	v_mov_b32_e32 v123, v122
	v_mov_b32_e32 v147, v146
	v_lshl_add_u64 v[164:165], s[2:3], 0, v[48:49]
	v_lshl_or_b32 v166, s5, 6, v182
	s_and_b32 s3, s4, 0xffffffc0
	v_add_u32_e32 v104, s8, v45
	v_add_u32_e32 v109, s8, v54
	v_add_u32_e32 v110, v55, v44
	s_mov_b32 s21, 0x3e6d3388
	s_mov_b32 s2, 0x3f07dc22
	s_mov_b32 s4, 0xbf3a00e3
	s_mov_b32 s8, 0x3f35f0e3
	s_mov_b32 s20, 0xbe11a98e
	s_mov_b32 s22, 0x3e027906
	v_mov_b32_e32 v113, 0x600
	s_branch .LBB0_756
; #define LAS __attribute__((address_space(3)))
; __device__ __forceinline__ unsigned pk2(float lo, float hi) { f32x2 v = {lo, hi}; nbf2 r = __builtin_convertvector(v, nbf2); return __builtin_bit_cast(unsigned, r); }
; #define WAVE_LDS_FENCE() asm volatile("s_waitcnt lgkmcnt(0)" ::: "memory")
; __device__ __forceinline__ float bf_at(const u32x4& lo, const u32x4& hi, int r) { const unsigned w = (r < 8 ? lo : hi)[(r & 7) >> 1]; return (r & 1) ? bf_hi(w) : bf_lo(w); }
; __device__ __forceinline__ void s5_out_phase(LAS unsigned char* lds, const bf16_t* UZ, const unsigned char* ws, const float* dskip, bf16_t* YG) {
;     ...
;         for (int mm = 0; mm < 4; ++mm) {
;             const int mf = mm, mb = 3 - mm;
; #pragma unroll
;             for (int nt = 0; nt < 8; ++nt) {
;                 const f32x4 z = {0.f, 0.f, 0.f, 0.f};
;                 const f32x4 cf = __builtin_amdgcn_mfma_f32_16x16x16bf16_1k(Uf[mf], Bf[0][nt], z, 0, 0, 0);
;                 const f32x4 cb = __builtin_amdgcn_mfma_f32_16x16x16bf16_1k(Uf[mb], Bf[1][nt], z, 0, 0, 0);
;                 u32x2 wf, wb; wf.x = pk2(cf[0], cf[1]); wf.y = pk2(cf[2], cf[3]); wb.x = pk2(cb[0], cb[1]); wb.y = pk2(cb[2], cb[3]);
;                 *(LAS u32x2*)(wl + nt * 640 + wofs) = wf;
;                 *(LAS u32x2*)(wl + BUT_BYTES + nt * 640 + wofs) = wb;
;             }
;             WAVE_LDS_FENCE();
;             const LAS unsigned char* rp = wl + lane * 80;
;             const u32x4 fre0 = *(const LAS u32x4*)(rp), fre1 = *(const LAS u32x4*)(rp + 16), fim0 = *(const LAS u32x4*)(rp + 32), fim1 = *(const LAS u32x4*)(rp + 48);
;             const u32x4 bre0 = *(const LAS u32x4*)(rp + BUT_BYTES), bre1 = *(const LAS u32x4*)(rp + BUT_BYTES + 16), bim0 = *(const LAS u32x4*)(rp + BUT_BYTES + 32), bim1 = *(const LAS u32x4*)(rp + BUT_BYTES + 48);
;             LAS unsigned char* xf = wl + 2 * BUT_BYTES; LAS unsigned char* xbk = xf + XB_BYTES;
; #pragma unroll
;             for (int rr = 0; rr < 16; ++rr) {
;                 const int r = rr, rb = 15 - rr;
;                 { const f32x2 bb = {bf_at(fre0, fre1, r), bf_at(fim0, fim1, r)};
;                   const f32x2 n2 = cmac((f32x2){xfr, xfi}, (f32x2){ap[0].x, ap[0].x}, (f32x2){-ap[0].y, ap[0].y}, bb); xfr = n2.x; xfi = n2.y;
;                   *(LAS unsigned*)(xf + r * XB_PITCH + lane * 4) = pk2(n2.x, n2.y); }
.LBB0_755:
	v_mov_b32_e32 v114, v44
	v_mov_b32_e32 v119, v45
	v_mov_b32_e32 v121, v46
	v_mov_b32_e32 v127, v47
	v_mfma_f32_4x4x4_16b_bf16 v[188:191], v[172:173], v[60:61], 0 cbsz:4 abid:0
	v_mfma_f32_4x4x4_16b_bf16 v[194:197], v[172:173], v[68:69], 0 cbsz:4 abid:0
	v_mfma_f32_4x4x4_16b_bf16 v[198:201], v[172:173], v[60:61], 0 cbsz:4 abid:1
	v_mfma_f32_4x4x4_16b_bf16 v[202:205], v[172:173], v[68:69], 0 cbsz:4 abid:1
	v_mfma_f32_4x4x4_16b_bf16 v[206:209], v[172:173], v[60:61], 0 cbsz:4 abid:2
	v_mfma_f32_4x4x4_16b_bf16 v[210:213], v[172:173], v[68:69], 0 cbsz:4 abid:2
	v_mfma_f32_4x4x4_16b_bf16 v[214:217], v[172:173], v[60:61], 0 cbsz:4 abid:3
	v_mfma_f32_4x4x4_16b_bf16 v[218:221], v[172:173], v[68:69], 0 cbsz:4 abid:3
	v_mfma_f32_4x4x4_16b_bf16 v[222:225], v[116:117], v[76:77], 0 cbsz:4 abid:0
	v_mfma_f32_4x4x4_16b_bf16 v[226:229], v[116:117], v[84:85], 0 cbsz:4 abid:0
	v_mfma_f32_4x4x4_16b_bf16 v[230:233], v[116:117], v[76:77], 0 cbsz:4 abid:1
	v_mfma_f32_4x4x4_16b_bf16 v[234:237], v[116:117], v[84:85], 0 cbsz:4 abid:1
	v_mfma_f32_4x4x4_16b_bf16 v[238:241], v[116:117], v[76:77], 0 cbsz:4 abid:2
	v_mfma_f32_4x4x4_16b_bf16 v[242:245], v[116:117], v[84:85], 0 cbsz:4 abid:2
	v_mfma_f32_4x4x4_16b_bf16 v[246:249], v[116:117], v[76:77], 0 cbsz:4 abid:3
	v_mfma_f32_4x4x4_16b_bf16 v[250:253], v[116:117], v[84:85], 0 cbsz:4 abid:3
	v_mfma_f32_4x4x4_16b_bf16 v[188:191], v[172:173], v[62:63], v[188:191] cbsz:4 abid:4
	v_mfma_f32_4x4x4_16b_bf16 v[194:197], v[172:173], v[70:71], v[194:197] cbsz:4 abid:4
	v_mfma_f32_4x4x4_16b_bf16 v[198:201], v[172:173], v[62:63], v[198:201] cbsz:4 abid:5
	v_mfma_f32_4x4x4_16b_bf16 v[202:205], v[172:173], v[70:71], v[202:205] cbsz:4 abid:5
	v_mfma_f32_4x4x4_16b_bf16 v[206:209], v[172:173], v[62:63], v[206:209] cbsz:4 abid:6
	v_mfma_f32_4x4x4_16b_bf16 v[210:213], v[172:173], v[70:71], v[210:213] cbsz:4 abid:6
	v_mfma_f32_4x4x4_16b_bf16 v[214:217], v[172:173], v[62:63], v[214:217] cbsz:4 abid:7
	v_mfma_f32_4x4x4_16b_bf16 v[218:221], v[172:173], v[70:71], v[218:221] cbsz:4 abid:7
	v_mfma_f32_4x4x4_16b_bf16 v[222:225], v[116:117], v[78:79], v[222:225] cbsz:4 abid:4
	v_mfma_f32_4x4x4_16b_bf16 v[226:229], v[116:117], v[86:87], v[226:229] cbsz:4 abid:4
	v_mfma_f32_4x4x4_16b_bf16 v[230:233], v[116:117], v[78:79], v[230:233] cbsz:4 abid:5
	v_mfma_f32_4x4x4_16b_bf16 v[234:237], v[116:117], v[86:87], v[234:237] cbsz:4 abid:5
	v_mfma_f32_4x4x4_16b_bf16 v[238:241], v[116:117], v[78:79], v[238:241] cbsz:4 abid:6
	v_mfma_f32_4x4x4_16b_bf16 v[242:245], v[116:117], v[86:87], v[242:245] cbsz:4 abid:6
	v_mfma_f32_4x4x4_16b_bf16 v[246:249], v[116:117], v[78:79], v[246:249] cbsz:4 abid:7
	v_mfma_f32_4x4x4_16b_bf16 v[250:253], v[116:117], v[86:87], v[250:253] cbsz:4 abid:7
	v_mfma_f32_4x4x4_16b_bf16 v[188:191], v[172:173], v[64:65], v[188:191] cbsz:4 abid:8
	v_mfma_f32_4x4x4_16b_bf16 v[194:197], v[172:173], v[72:73], v[194:197] cbsz:4 abid:8
	v_mfma_f32_4x4x4_16b_bf16 v[198:201], v[172:173], v[64:65], v[198:201] cbsz:4 abid:9
	v_mfma_f32_4x4x4_16b_bf16 v[202:205], v[172:173], v[72:73], v[202:205] cbsz:4 abid:9
	v_mfma_f32_4x4x4_16b_bf16 v[206:209], v[172:173], v[64:65], v[206:209] cbsz:4 abid:10
	v_mfma_f32_4x4x4_16b_bf16 v[210:213], v[172:173], v[72:73], v[210:213] cbsz:4 abid:10
	v_mfma_f32_4x4x4_16b_bf16 v[214:217], v[172:173], v[64:65], v[214:217] cbsz:4 abid:11
	v_mfma_f32_4x4x4_16b_bf16 v[218:221], v[172:173], v[72:73], v[218:221] cbsz:4 abid:11
	v_mfma_f32_4x4x4_16b_bf16 v[222:225], v[116:117], v[80:81], v[222:225] cbsz:4 abid:8
	v_mfma_f32_4x4x4_16b_bf16 v[226:229], v[116:117], v[88:89], v[226:229] cbsz:4 abid:8
	v_mfma_f32_4x4x4_16b_bf16 v[230:233], v[116:117], v[80:81], v[230:233] cbsz:4 abid:9
	v_mfma_f32_4x4x4_16b_bf16 v[234:237], v[116:117], v[88:89], v[234:237] cbsz:4 abid:9
	v_mfma_f32_4x4x4_16b_bf16 v[238:241], v[116:117], v[80:81], v[238:241] cbsz:4 abid:10
	v_mfma_f32_4x4x4_16b_bf16 v[242:245], v[116:117], v[88:89], v[242:245] cbsz:4 abid:10
	v_mfma_f32_4x4x4_16b_bf16 v[246:249], v[116:117], v[80:81], v[246:249] cbsz:4 abid:11
	v_mfma_f32_4x4x4_16b_bf16 v[250:253], v[116:117], v[88:89], v[250:253] cbsz:4 abid:11
	v_mfma_f32_4x4x4_16b_bf16 v[188:191], v[172:173], v[66:67], v[188:191] cbsz:4 abid:12
	v_mfma_f32_4x4x4_16b_bf16 v[194:197], v[172:173], v[74:75], v[194:197] cbsz:4 abid:12
	v_mfma_f32_4x4x4_16b_bf16 v[198:201], v[172:173], v[66:67], v[198:201] cbsz:4 abid:13
	v_mfma_f32_4x4x4_16b_bf16 v[202:205], v[172:173], v[74:75], v[202:205] cbsz:4 abid:13
	v_mfma_f32_4x4x4_16b_bf16 v[206:209], v[172:173], v[66:67], v[206:209] cbsz:4 abid:14
	v_mfma_f32_4x4x4_16b_bf16 v[210:213], v[172:173], v[74:75], v[210:213] cbsz:4 abid:14
	v_mfma_f32_4x4x4_16b_bf16 v[214:217], v[172:173], v[66:67], v[214:217] cbsz:4 abid:15
	v_mfma_f32_4x4x4_16b_bf16 v[218:221], v[172:173], v[74:75], v[218:221] cbsz:4 abid:15
	v_mfma_f32_4x4x4_16b_bf16 v[222:225], v[116:117], v[82:83], v[222:225] cbsz:4 abid:12
	v_mfma_f32_4x4x4_16b_bf16 v[226:229], v[116:117], v[90:91], v[226:229] cbsz:4 abid:12
	v_mfma_f32_4x4x4_16b_bf16 v[230:233], v[116:117], v[82:83], v[230:233] cbsz:4 abid:13
	v_mfma_f32_4x4x4_16b_bf16 v[234:237], v[116:117], v[90:91], v[234:237] cbsz:4 abid:13
	v_mfma_f32_4x4x4_16b_bf16 v[238:241], v[116:117], v[82:83], v[238:241] cbsz:4 abid:14
	v_mfma_f32_4x4x4_16b_bf16 v[242:245], v[116:117], v[90:91], v[242:245] cbsz:4 abid:14
	v_mfma_f32_4x4x4_16b_bf16 v[246:249], v[116:117], v[82:83], v[246:249] cbsz:4 abid:15
	v_mfma_f32_4x4x4_16b_bf16 v[250:253], v[116:117], v[90:91], v[250:253] cbsz:4 abid:15
	v_fma_f32 v188, v150, v114, v188
	v_fma_f32 v194, v150, v119, v194
	v_fma_f32 v188, v16, v119, v188
	v_fma_f32 v194, v17, v114, v194
; #define LAS __attribute__((address_space(3)))
; __device__ __forceinline__ unsigned pk2(float lo, float hi) { f32x2 v = {lo, hi}; nbf2 r = __builtin_convertvector(v, nbf2); return __builtin_bit_cast(unsigned, r); }
; #define WAVE_LDS_FENCE() asm volatile("s_waitcnt lgkmcnt(0)" ::: "memory")
; __device__ __forceinline__ float bf_at(const u32x4& lo, const u32x4& hi, int r) { const unsigned w = (r < 8 ? lo : hi)[(r & 7) >> 1]; return (r & 1) ? bf_hi(w) : bf_lo(w); }
; __device__ __forceinline__ void s5_out_phase(LAS unsigned char* lds, const bf16_t* UZ, const unsigned char* ws, const float* dskip, bf16_t* YG) {
;     ...
; #pragma unroll
;             for (int rr = 0; rr < 16; ++rr) {
;                 const int r = rr, rb = 15 - rr;
;                 { const f32x2 bb = {bf_at(fre0, fre1, r), bf_at(fim0, fim1, r)};
;                   const f32x2 n2 = cmac((f32x2){xfr, xfi}, (f32x2){ap[0].x, ap[0].x}, (f32x2){-ap[0].y, ap[0].y}, bb); xfr = n2.x; xfi = n2.y;
;                   *(LAS unsigned*)(xf + r * XB_PITCH + lane * 4) = pk2(n2.x, n2.y); }
;                 { const f32x2 bb = {bf_at(bre0, bre1, rb), bf_at(bim0, bim1, rb)};
;                   const f32x2 n2 = cmac((f32x2){xbr, xbi}, (f32x2){ap[1].x, ap[1].x}, (f32x2){-ap[1].y, ap[1].y}, bb); xbr = n2.x; xbi = n2.y;
;                   *(LAS unsigned*)(xbk + rb * XB_PITCH + lane * 4) = pk2(n2.x, n2.y); }
;             }
;             WAVE_LDS_FENCE();
; #pragma unroll
;             for (int ks = 0; ks < 4; ++ks) {
;                 const bf16x8 Xf = *(const LAS bf16x8*)(xf + fr * XB_PITCH + (8 * fq + 32 * ks) * 2);
	v_fma_f32 v249, v152, v121, v249
	v_fma_f32 v253, v152, v127, v253
	v_fma_f32 v249, v36, v127, v249
	v_fma_f32 v253, v37, v121, v253
	v_cvt_pk_bf16_f32 v128, v188, v194
	v_cvt_pk_bf16_f32 v136, v249, v253
	ds_write_b32 v103, v128 offset:10240
	ds_write_b32 v103, v136 offset:18672
	v_fma_f32 v189, v150, v188, v189
	v_fma_f32 v195, v150, v194, v195
	v_fma_f32 v189, v16, v194, v189
	v_fma_f32 v195, v17, v188, v195
	v_fma_f32 v248, v152, v249, v248
	v_fma_f32 v252, v152, v253, v252
	v_fma_f32 v248, v36, v253, v248
	v_fma_f32 v252, v37, v249, v252
	v_cvt_pk_bf16_f32 v131, v189, v195
	v_cvt_pk_bf16_f32 v139, v248, v252
	ds_write_b32 v103, v131 offset:10512
	ds_write_b32 v103, v139 offset:18400
	v_fma_f32 v190, v150, v189, v190
	v_fma_f32 v196, v150, v195, v196
	v_fma_f32 v190, v16, v195, v190
	v_fma_f32 v196, v17, v189, v196
	v_fma_f32 v247, v152, v248, v247
	v_fma_f32 v251, v152, v252, v251
	v_fma_f32 v247, v36, v252, v247
	v_fma_f32 v251, v37, v248, v251
	v_cvt_pk_bf16_f32 v132, v190, v196
	v_cvt_pk_bf16_f32 v143, v247, v251
	ds_write_b32 v103, v132 offset:10784
	ds_write_b32 v103, v143 offset:18128
	v_fma_f32 v191, v150, v190, v191
	v_fma_f32 v197, v150, v196, v197
	v_fma_f32 v191, v16, v196, v191
	v_fma_f32 v197, v17, v190, v197
	v_fma_f32 v246, v152, v247, v246
	v_fma_f32 v250, v152, v251, v250
	v_fma_f32 v246, v36, v251, v246
	v_fma_f32 v250, v37, v247, v250
	v_cvt_pk_bf16_f32 v135, v191, v197
	v_cvt_pk_bf16_f32 v187, v246, v250
	ds_write_b32 v103, v135 offset:11056
	ds_write_b32 v103, v187 offset:17856
	v_fma_f32 v198, v150, v191, v198
	v_fma_f32 v202, v150, v197, v202
	v_fma_f32 v198, v16, v197, v198
	v_fma_f32 v202, v17, v191, v202
	v_fma_f32 v241, v152, v246, v241
	v_fma_f32 v245, v152, v250, v245
	v_fma_f32 v241, v36, v250, v241
	v_fma_f32 v245, v37, v246, v245
	v_cvt_pk_bf16_f32 v128, v198, v202
	v_cvt_pk_bf16_f32 v136, v241, v245
	ds_write_b32 v103, v128 offset:11328
	ds_write_b32 v103, v136 offset:17584
	v_fma_f32 v199, v150, v198, v199
	v_fma_f32 v203, v150, v202, v203
	v_fma_f32 v199, v16, v202, v199
	v_fma_f32 v203, v17, v198, v203
	v_fma_f32 v240, v152, v241, v240
	v_fma_f32 v244, v152, v245, v244
	v_fma_f32 v240, v36, v245, v240
	v_fma_f32 v244, v37, v241, v244
	v_cvt_pk_bf16_f32 v131, v199, v203
	v_cvt_pk_bf16_f32 v139, v240, v244
	ds_write_b32 v103, v131 offset:11600
	ds_write_b32 v103, v139 offset:17312
	v_fma_f32 v200, v150, v199, v200
	v_fma_f32 v204, v150, v203, v204
	v_fma_f32 v200, v16, v203, v200
	v_fma_f32 v204, v17, v199, v204
	v_fma_f32 v239, v152, v240, v239
	v_fma_f32 v243, v152, v244, v243
	v_fma_f32 v239, v36, v244, v239
	v_fma_f32 v243, v37, v240, v243
	v_cvt_pk_bf16_f32 v132, v200, v204
	v_cvt_pk_bf16_f32 v143, v239, v243
	ds_write_b32 v103, v132 offset:11872
	ds_write_b32 v103, v143 offset:17040
	v_fma_f32 v201, v150, v200, v201
	v_fma_f32 v205, v150, v204, v205
	v_fma_f32 v201, v16, v204, v201
	v_fma_f32 v205, v17, v200, v205
	v_fma_f32 v238, v152, v239, v238
	v_fma_f32 v242, v152, v243, v242
	v_fma_f32 v238, v36, v243, v238
	v_fma_f32 v242, v37, v239, v242
	v_cvt_pk_bf16_f32 v135, v201, v205
	v_cvt_pk_bf16_f32 v187, v238, v242
	ds_write_b32 v103, v135 offset:12144
	ds_write_b32 v103, v187 offset:16768
	v_fma_f32 v206, v150, v201, v206
	v_fma_f32 v210, v150, v205, v210
	v_fma_f32 v206, v16, v205, v206
	v_fma_f32 v210, v17, v201, v210
	v_fma_f32 v233, v152, v238, v233
	v_fma_f32 v237, v152, v242, v237
	v_fma_f32 v233, v36, v242, v233
	v_fma_f32 v237, v37, v238, v237
	v_cvt_pk_bf16_f32 v128, v206, v210
	v_cvt_pk_bf16_f32 v136, v233, v237
	ds_write_b32 v103, v128 offset:12416
	ds_write_b32 v103, v136 offset:16496
	v_fma_f32 v207, v150, v206, v207
	v_fma_f32 v211, v150, v210, v211
	v_fma_f32 v207, v16, v210, v207
	v_fma_f32 v211, v17, v206, v211
	v_fma_f32 v232, v152, v233, v232
	v_fma_f32 v236, v152, v237, v236
	v_fma_f32 v232, v36, v237, v232
	v_fma_f32 v236, v37, v233, v236
	v_cvt_pk_bf16_f32 v131, v207, v211
	v_cvt_pk_bf16_f32 v139, v232, v236
	ds_write_b32 v103, v131 offset:12688
	ds_write_b32 v103, v139 offset:16224
	v_fma_f32 v208, v150, v207, v208
	v_fma_f32 v212, v150, v211, v212
	v_fma_f32 v208, v16, v211, v208
	v_fma_f32 v212, v17, v207, v212
	v_fma_f32 v231, v152, v232, v231
	v_fma_f32 v235, v152, v236, v235
	v_fma_f32 v231, v36, v236, v231
	v_fma_f32 v235, v37, v232, v235
	v_cvt_pk_bf16_f32 v132, v208, v212
	v_cvt_pk_bf16_f32 v143, v231, v235
	ds_write_b32 v103, v132 offset:12960
	ds_write_b32 v103, v143 offset:15952
	v_fma_f32 v209, v150, v208, v209
	v_fma_f32 v213, v150, v212, v213
	v_fma_f32 v209, v16, v212, v209
	v_fma_f32 v213, v17, v208, v213
	v_fma_f32 v230, v152, v231, v230
	v_fma_f32 v234, v152, v235, v234
	v_fma_f32 v230, v36, v235, v230
	v_fma_f32 v234, v37, v231, v234
	v_cvt_pk_bf16_f32 v135, v209, v213
	v_cvt_pk_bf16_f32 v187, v230, v234
	ds_write_b32 v103, v135 offset:13232
	ds_write_b32 v103, v187 offset:15680
	v_fma_f32 v214, v150, v209, v214
	v_fma_f32 v218, v150, v213, v218
	v_fma_f32 v214, v16, v213, v214
	v_fma_f32 v218, v17, v209, v218
	v_fma_f32 v225, v152, v230, v225
	v_fma_f32 v229, v152, v234, v229
	v_fma_f32 v225, v36, v234, v225
	v_fma_f32 v229, v37, v230, v229
	v_cvt_pk_bf16_f32 v128, v214, v218
	v_cvt_pk_bf16_f32 v136, v225, v229
	ds_write_b32 v103, v128 offset:13504
	ds_write_b32 v103, v136 offset:15408
	v_fma_f32 v215, v150, v214, v215
	v_fma_f32 v219, v150, v218, v219
	v_fma_f32 v215, v16, v218, v215
	v_fma_f32 v219, v17, v214, v219
	v_fma_f32 v224, v152, v225, v224
	v_fma_f32 v228, v152, v229, v228
	v_fma_f32 v224, v36, v229, v224
	v_fma_f32 v228, v37, v225, v228
	v_cvt_pk_bf16_f32 v131, v215, v219
	v_cvt_pk_bf16_f32 v139, v224, v228
	ds_write_b32 v103, v131 offset:13776
	ds_write_b32 v103, v139 offset:15136
	v_fma_f32 v216, v150, v215, v216
	v_fma_f32 v220, v150, v219, v220
	v_fma_f32 v216, v16, v219, v216
	v_fma_f32 v220, v17, v215, v220
	v_fma_f32 v223, v152, v224, v223
	v_fma_f32 v227, v152, v228, v227
	v_fma_f32 v223, v36, v228, v223
	v_fma_f32 v227, v37, v224, v227
	v_cvt_pk_bf16_f32 v132, v216, v220
	v_cvt_pk_bf16_f32 v143, v223, v227
	ds_write_b32 v103, v132 offset:14048
	ds_write_b32 v103, v143 offset:14864
	v_fma_f32 v217, v150, v216, v217
	v_fma_f32 v221, v150, v220, v221
	v_fma_f32 v217, v16, v220, v217
	v_fma_f32 v221, v17, v216, v221
	v_fma_f32 v222, v152, v223, v222
	v_fma_f32 v226, v152, v227, v226
	v_fma_f32 v222, v36, v227, v222
	v_fma_f32 v226, v37, v223, v226
	v_cvt_pk_bf16_f32 v135, v217, v221
	v_cvt_pk_bf16_f32 v187, v222, v226
	ds_write_b32 v103, v135 offset:14320
	ds_write_b32 v103, v187 offset:14592
	v_mov_b32_e32 v114, v217
	v_mov_b32_e32 v119, v221
	v_mov_b32_e32 v121, v222
	v_mov_b32_e32 v127, v226
	ds_read_b128 v[188:191], v110 offset:10240
	ds_read_b128 v[194:197], v110 offset:10304
	ds_read_b128 v[198:201], v110 offset:10368
	ds_read_b128 v[202:205], v110 offset:10432
	ds_read_b128 v[206:209], v110 offset:14592
	ds_read_b128 v[210:213], v110 offset:14656
	ds_read_b128 v[214:217], v110 offset:14720
	ds_read_b128 v[218:221], v110 offset:14784
	s_waitcnt lgkmcnt(7)
; #define LAS __attribute__((address_space(3)))
; __device__ __forceinline__ unsigned pk2(float lo, float hi) { f32x2 v = {lo, hi}; nbf2 r = __builtin_convertvector(v, nbf2); return __builtin_bit_cast(unsigned, r); }
; __device__ __forceinline__ void s5_out_phase(LAS unsigned char* lds, const bf16_t* UZ, const unsigned char* ws, const float* dskip, bf16_t* YG) {
;     ...
;         for (int mm = 0; mm < 4; ++mm) {
;             const int mf = mm, mb = 3 - mm;
; #pragma unroll
;             for (int nt = 0; nt < 8; ++nt) {
;                 const f32x4 z = {0.f, 0.f, 0.f, 0.f};
;                 const f32x4 cf = __builtin_amdgcn_mfma_f32_16x16x16bf16_1k(Uf[mf], Bf[0][nt], z, 0, 0, 0);
;                 const f32x4 cb = __builtin_amdgcn_mfma_f32_16x16x16bf16_1k(Uf[mb], Bf[1][nt], z, 0, 0, 0);
;                 u32x2 wf, wb; wf.x = pk2(cf[0], cf[1]); wf.y = pk2(cf[2], cf[3]); wb.x = pk2(cb[0], cb[1]); wb.y = pk2(cb[2], cb[3]);
;                 *(LAS u32x2*)(wl + nt * 640 + wofs) = wf;
;                 *(LAS u32x2*)(wl + BUT_BYTES + nt * 640 + wofs) = wb;
;     ...
; #pragma unroll
;             for (int ks = 0; ks < 4; ++ks) {
;                 const bf16x8 Xf = *(const LAS bf16x8*)(xf + fr * XB_PITCH + (8 * fq + 32 * ks) * 2);
;                 const bf16x8 Xb = *(const LAS bf16x8*)(xbk + fr * XB_PITCH + (8 * fq + 32 * ks) * 2);
;                 accY[mf] = __builtin_amdgcn_mfma_f32_16x16x32_bf16(Cf[0][ks], Xf, accY[mf], 0, 0, 0);
;                 accY[mb] = __builtin_amdgcn_mfma_f32_16x16x32_bf16(Cf[1][ks], Xb, accY[mb], 0, 0, 0);
;             }
	v_mfma_f32_16x16x32_bf16 v[48:51], v[0:3], v[188:191], 0
	s_waitcnt lgkmcnt(3)
	v_mfma_f32_16x16x32_bf16 v[44:47], v[20:23], v[206:209], 0
	v_mfma_f32_16x16x32_bf16 v[48:51], v[4:7], v[194:197], v[48:51]
	s_waitcnt lgkmcnt(2)
	v_mfma_f32_16x16x32_bf16 v[44:47], v[24:27], v[210:213], v[44:47]
	v_mfma_f32_16x16x32_bf16 v[48:51], v[8:11], v[198:201], v[48:51]
	s_waitcnt lgkmcnt(1)
	v_mfma_f32_16x16x32_bf16 v[44:47], v[28:31], v[214:217], v[44:47]
	v_mfma_f32_16x16x32_bf16 v[48:51], v[12:15], v[202:205], v[48:51]
	s_waitcnt lgkmcnt(0)
	v_mfma_f32_16x16x32_bf16 v[44:47], v[32:35], v[218:221], v[44:47]
	v_mfma_f32_4x4x4_16b_bf16 v[188:191], v[170:171], v[60:61], 0 cbsz:4 abid:0
	v_mfma_f32_4x4x4_16b_bf16 v[194:197], v[170:171], v[68:69], 0 cbsz:4 abid:0
	v_mfma_f32_4x4x4_16b_bf16 v[198:201], v[170:171], v[60:61], 0 cbsz:4 abid:1
	v_mfma_f32_4x4x4_16b_bf16 v[202:205], v[170:171], v[68:69], 0 cbsz:4 abid:1
	v_mfma_f32_4x4x4_16b_bf16 v[206:209], v[170:171], v[60:61], 0 cbsz:4 abid:2
	v_mfma_f32_4x4x4_16b_bf16 v[210:213], v[170:171], v[68:69], 0 cbsz:4 abid:2
	v_mfma_f32_4x4x4_16b_bf16 v[214:217], v[170:171], v[60:61], 0 cbsz:4 abid:3
	v_mfma_f32_4x4x4_16b_bf16 v[218:221], v[170:171], v[68:69], 0 cbsz:4 abid:3
	v_mfma_f32_4x4x4_16b_bf16 v[222:225], v[168:169], v[76:77], 0 cbsz:4 abid:0
	v_mfma_f32_4x4x4_16b_bf16 v[226:229], v[168:169], v[84:85], 0 cbsz:4 abid:0
	v_mfma_f32_4x4x4_16b_bf16 v[230:233], v[168:169], v[76:77], 0 cbsz:4 abid:1
	v_mfma_f32_4x4x4_16b_bf16 v[234:237], v[168:169], v[84:85], 0 cbsz:4 abid:1
	v_mfma_f32_4x4x4_16b_bf16 v[238:241], v[168:169], v[76:77], 0 cbsz:4 abid:2
	v_mfma_f32_4x4x4_16b_bf16 v[242:245], v[168:169], v[84:85], 0 cbsz:4 abid:2
	v_mfma_f32_4x4x4_16b_bf16 v[246:249], v[168:169], v[76:77], 0 cbsz:4 abid:3
	v_mfma_f32_4x4x4_16b_bf16 v[250:253], v[168:169], v[84:85], 0 cbsz:4 abid:3
	v_mfma_f32_4x4x4_16b_bf16 v[188:191], v[170:171], v[62:63], v[188:191] cbsz:4 abid:4
	v_mfma_f32_4x4x4_16b_bf16 v[194:197], v[170:171], v[70:71], v[194:197] cbsz:4 abid:4
	v_mfma_f32_4x4x4_16b_bf16 v[198:201], v[170:171], v[62:63], v[198:201] cbsz:4 abid:5
	v_mfma_f32_4x4x4_16b_bf16 v[202:205], v[170:171], v[70:71], v[202:205] cbsz:4 abid:5
	v_mfma_f32_4x4x4_16b_bf16 v[206:209], v[170:171], v[62:63], v[206:209] cbsz:4 abid:6
	v_mfma_f32_4x4x4_16b_bf16 v[210:213], v[170:171], v[70:71], v[210:213] cbsz:4 abid:6
	v_mfma_f32_4x4x4_16b_bf16 v[214:217], v[170:171], v[62:63], v[214:217] cbsz:4 abid:7
	v_mfma_f32_4x4x4_16b_bf16 v[218:221], v[170:171], v[70:71], v[218:221] cbsz:4 abid:7
	v_mfma_f32_4x4x4_16b_bf16 v[222:225], v[168:169], v[78:79], v[222:225] cbsz:4 abid:4
	v_mfma_f32_4x4x4_16b_bf16 v[226:229], v[168:169], v[86:87], v[226:229] cbsz:4 abid:4
	v_mfma_f32_4x4x4_16b_bf16 v[230:233], v[168:169], v[78:79], v[230:233] cbsz:4 abid:5
	v_mfma_f32_4x4x4_16b_bf16 v[234:237], v[168:169], v[86:87], v[234:237] cbsz:4 abid:5
	v_mfma_f32_4x4x4_16b_bf16 v[238:241], v[168:169], v[78:79], v[238:241] cbsz:4 abid:6
	v_mfma_f32_4x4x4_16b_bf16 v[242:245], v[168:169], v[86:87], v[242:245] cbsz:4 abid:6
	v_mfma_f32_4x4x4_16b_bf16 v[246:249], v[168:169], v[78:79], v[246:249] cbsz:4 abid:7
	v_mfma_f32_4x4x4_16b_bf16 v[250:253], v[168:169], v[86:87], v[250:253] cbsz:4 abid:7
	v_mfma_f32_4x4x4_16b_bf16 v[188:191], v[170:171], v[64:65], v[188:191] cbsz:4 abid:8
	v_mfma_f32_4x4x4_16b_bf16 v[194:197], v[170:171], v[72:73], v[194:197] cbsz:4 abid:8
	v_mfma_f32_4x4x4_16b_bf16 v[198:201], v[170:171], v[64:65], v[198:201] cbsz:4 abid:9
	v_mfma_f32_4x4x4_16b_bf16 v[202:205], v[170:171], v[72:73], v[202:205] cbsz:4 abid:9
	v_mfma_f32_4x4x4_16b_bf16 v[206:209], v[170:171], v[64:65], v[206:209] cbsz:4 abid:10
	v_mfma_f32_4x4x4_16b_bf16 v[210:213], v[170:171], v[72:73], v[210:213] cbsz:4 abid:10
	v_mfma_f32_4x4x4_16b_bf16 v[214:217], v[170:171], v[64:65], v[214:217] cbsz:4 abid:11
	v_mfma_f32_4x4x4_16b_bf16 v[218:221], v[170:171], v[72:73], v[218:221] cbsz:4 abid:11
	v_mfma_f32_4x4x4_16b_bf16 v[222:225], v[168:169], v[80:81], v[222:225] cbsz:4 abid:8
	v_mfma_f32_4x4x4_16b_bf16 v[226:229], v[168:169], v[88:89], v[226:229] cbsz:4 abid:8
	v_mfma_f32_4x4x4_16b_bf16 v[230:233], v[168:169], v[80:81], v[230:233] cbsz:4 abid:9
	v_mfma_f32_4x4x4_16b_bf16 v[234:237], v[168:169], v[88:89], v[234:237] cbsz:4 abid:9
	v_mfma_f32_4x4x4_16b_bf16 v[238:241], v[168:169], v[80:81], v[238:241] cbsz:4 abid:10
	v_mfma_f32_4x4x4_16b_bf16 v[242:245], v[168:169], v[88:89], v[242:245] cbsz:4 abid:10
	v_mfma_f32_4x4x4_16b_bf16 v[246:249], v[168:169], v[80:81], v[246:249] cbsz:4 abid:11
	v_mfma_f32_4x4x4_16b_bf16 v[250:253], v[168:169], v[88:89], v[250:253] cbsz:4 abid:11
	v_mfma_f32_4x4x4_16b_bf16 v[188:191], v[170:171], v[66:67], v[188:191] cbsz:4 abid:12
	v_mfma_f32_4x4x4_16b_bf16 v[194:197], v[170:171], v[74:75], v[194:197] cbsz:4 abid:12
	v_mfma_f32_4x4x4_16b_bf16 v[198:201], v[170:171], v[66:67], v[198:201] cbsz:4 abid:13
	v_mfma_f32_4x4x4_16b_bf16 v[202:205], v[170:171], v[74:75], v[202:205] cbsz:4 abid:13
	v_mfma_f32_4x4x4_16b_bf16 v[206:209], v[170:171], v[66:67], v[206:209] cbsz:4 abid:14
	v_mfma_f32_4x4x4_16b_bf16 v[210:213], v[170:171], v[74:75], v[210:213] cbsz:4 abid:14
	v_mfma_f32_4x4x4_16b_bf16 v[214:217], v[170:171], v[66:67], v[214:217] cbsz:4 abid:15
	v_mfma_f32_4x4x4_16b_bf16 v[218:221], v[170:171], v[74:75], v[218:221] cbsz:4 abid:15
	v_mfma_f32_4x4x4_16b_bf16 v[222:225], v[168:169], v[82:83], v[222:225] cbsz:4 abid:12
	v_mfma_f32_4x4x4_16b_bf16 v[226:229], v[168:169], v[90:91], v[226:229] cbsz:4 abid:12
	v_mfma_f32_4x4x4_16b_bf16 v[230:233], v[168:169], v[82:83], v[230:233] cbsz:4 abid:13
	v_mfma_f32_4x4x4_16b_bf16 v[234:237], v[168:169], v[90:91], v[234:237] cbsz:4 abid:13
; #define LAS __attribute__((address_space(3)))
; #define WAVE_LDS_FENCE() asm volatile("s_waitcnt lgkmcnt(0)" ::: "memory")
; __device__ __forceinline__ void s5_out_phase(LAS unsigned char* lds, const bf16_t* UZ, const unsigned char* ws, const float* dskip, bf16_t* YG) {
;     ...
;         for (int mm = 0; mm < 4; ++mm) {
;             const int mf = mm, mb = 3 - mm;
; #pragma unroll
;             for (int nt = 0; nt < 8; ++nt) {
;                 const f32x4 z = {0.f, 0.f, 0.f, 0.f};
;                 const f32x4 cf = __builtin_amdgcn_mfma_f32_16x16x16bf16_1k(Uf[mf], Bf[0][nt], z, 0, 0, 0);
;                 const f32x4 cb = __builtin_amdgcn_mfma_f32_16x16x16bf16_1k(Uf[mb], Bf[1][nt], z, 0, 0, 0);
;                 u32x2 wf, wb; wf.x = pk2(cf[0], cf[1]); wf.y = pk2(cf[2], cf[3]); wb.x = pk2(cb[0], cb[1]); wb.y = pk2(cb[2], cb[3]);
;                 *(LAS u32x2*)(wl + nt * 640 + wofs) = wf;
;                 *(LAS u32x2*)(wl + BUT_BYTES + nt * 640 + wofs) = wb;
;             }
;             WAVE_LDS_FENCE();
;             const LAS unsigned char* rp = wl + lane * 80;
;             const u32x4 fre0 = *(const LAS u32x4*)(rp), fre1 = *(const LAS u32x4*)(rp + 16), fim0 = *(const LAS u32x4*)(rp + 32), fim1 = *(const LAS u32x4*)(rp + 48);
;             const u32x4 bre0 = *(const LAS u32x4*)(rp + BUT_BYTES), bre1 = *(const LAS u32x4*)(rp + BUT_BYTES + 16), bim0 = *(const LAS u32x4*)(rp + BUT_BYTES + 32), bim1 = *(const LAS u32x4*)(rp + BUT_BYTES + 48);
;             LAS unsigned char* xf = wl + 2 * BUT_BYTES; LAS unsigned char* xbk = xf + XB_BYTES;
; #pragma unroll
;             for (int rr = 0; rr < 16; ++rr) {
;                 const int r = rr, rb = 15 - rr;
;                 { const f32x2 bb = {bf_at(fre0, fre1, r), bf_at(fim0, fim1, r)};
;                   const f32x2 n2 = cmac((f32x2){xfr, xfi}, (f32x2){ap[0].x, ap[0].x}, (f32x2){-ap[0].y, ap[0].y}, bb); xfr = n2.x; xfi = n2.y;
;                   *(LAS unsigned*)(xf + r * XB_PITCH + lane * 4) = pk2(n2.x, n2.y); }
;                 { const f32x2 bb = {bf_at(bre0, bre1, rb), bf_at(bim0, bim1, rb)};
;                   const f32x2 n2 = cmac((f32x2){xbr, xbi}, (f32x2){ap[1].x, ap[1].x}, (f32x2){-ap[1].y, ap[1].y}, bb); xbr = n2.x; xbi = n2.y;
;                   *(LAS unsigned*)(xbk + rb * XB_PITCH + lane * 4) = pk2(n2.x, n2.y); }
;             }
	v_mfma_f32_4x4x4_16b_bf16 v[238:241], v[168:169], v[82:83], v[238:241] cbsz:4 abid:14
	v_mfma_f32_4x4x4_16b_bf16 v[242:245], v[168:169], v[90:91], v[242:245] cbsz:4 abid:14
	v_mfma_f32_4x4x4_16b_bf16 v[246:249], v[168:169], v[82:83], v[246:249] cbsz:4 abid:15
	v_mfma_f32_4x4x4_16b_bf16 v[250:253], v[168:169], v[90:91], v[250:253] cbsz:4 abid:15
	v_fma_f32 v188, v150, v114, v188
	v_fma_f32 v194, v150, v119, v194
	v_fma_f32 v188, v16, v119, v188
	v_fma_f32 v194, v17, v114, v194
	v_fma_f32 v249, v152, v121, v249
	v_fma_f32 v253, v152, v127, v253
	v_fma_f32 v249, v36, v127, v249
	v_fma_f32 v253, v37, v121, v253
	v_cvt_pk_bf16_f32 v128, v188, v194
	v_cvt_pk_bf16_f32 v136, v249, v253
	ds_write_b32 v103, v128 offset:10240
	ds_write_b32 v103, v136 offset:18672
	v_fma_f32 v189, v150, v188, v189
	v_fma_f32 v195, v150, v194, v195
	v_fma_f32 v189, v16, v194, v189
	v_fma_f32 v195, v17, v188, v195
	v_fma_f32 v248, v152, v249, v248
	v_fma_f32 v252, v152, v253, v252
	v_fma_f32 v248, v36, v253, v248
	v_fma_f32 v252, v37, v249, v252
	v_cvt_pk_bf16_f32 v131, v189, v195
	v_cvt_pk_bf16_f32 v139, v248, v252
	ds_write_b32 v103, v131 offset:10512
	ds_write_b32 v103, v139 offset:18400
	v_fma_f32 v190, v150, v189, v190
	v_fma_f32 v196, v150, v195, v196
	v_fma_f32 v190, v16, v195, v190
	v_fma_f32 v196, v17, v189, v196
	v_fma_f32 v247, v152, v248, v247
	v_fma_f32 v251, v152, v252, v251
	v_fma_f32 v247, v36, v252, v247
	v_fma_f32 v251, v37, v248, v251
	v_cvt_pk_bf16_f32 v132, v190, v196
	v_cvt_pk_bf16_f32 v143, v247, v251
	ds_write_b32 v103, v132 offset:10784
	ds_write_b32 v103, v143 offset:18128
	v_fma_f32 v191, v150, v190, v191
	v_fma_f32 v197, v150, v196, v197
	v_fma_f32 v191, v16, v196, v191
	v_fma_f32 v197, v17, v190, v197
	v_fma_f32 v246, v152, v247, v246
	v_fma_f32 v250, v152, v251, v250
	v_fma_f32 v246, v36, v251, v246
	v_fma_f32 v250, v37, v247, v250
	v_cvt_pk_bf16_f32 v135, v191, v197
	v_cvt_pk_bf16_f32 v187, v246, v250
	ds_write_b32 v103, v135 offset:11056
	ds_write_b32 v103, v187 offset:17856
	v_fma_f32 v198, v150, v191, v198
	v_fma_f32 v202, v150, v197, v202
	v_fma_f32 v198, v16, v197, v198
	v_fma_f32 v202, v17, v191, v202
	v_fma_f32 v241, v152, v246, v241
	v_fma_f32 v245, v152, v250, v245
	v_fma_f32 v241, v36, v250, v241
	v_fma_f32 v245, v37, v246, v245
	v_cvt_pk_bf16_f32 v128, v198, v202
	v_cvt_pk_bf16_f32 v136, v241, v245
	ds_write_b32 v103, v128 offset:11328
	ds_write_b32 v103, v136 offset:17584
	v_fma_f32 v199, v150, v198, v199
	v_fma_f32 v203, v150, v202, v203
	v_fma_f32 v199, v16, v202, v199
	v_fma_f32 v203, v17, v198, v203
	v_fma_f32 v240, v152, v241, v240
	v_fma_f32 v244, v152, v245, v244
	v_fma_f32 v240, v36, v245, v240
	v_fma_f32 v244, v37, v241, v244
	v_cvt_pk_bf16_f32 v131, v199, v203
	v_cvt_pk_bf16_f32 v139, v240, v244
	ds_write_b32 v103, v131 offset:11600
	ds_write_b32 v103, v139 offset:17312
	v_fma_f32 v200, v150, v199, v200
	v_fma_f32 v204, v150, v203, v204
	v_fma_f32 v200, v16, v203, v200
	v_fma_f32 v204, v17, v199, v204
	v_fma_f32 v239, v152, v240, v239
	v_fma_f32 v243, v152, v244, v243
	v_fma_f32 v239, v36, v244, v239
	v_fma_f32 v243, v37, v240, v243
	v_cvt_pk_bf16_f32 v132, v200, v204
	v_cvt_pk_bf16_f32 v143, v239, v243
	ds_write_b32 v103, v132 offset:11872
	ds_write_b32 v103, v143 offset:17040
	v_fma_f32 v201, v150, v200, v201
	v_fma_f32 v205, v150, v204, v205
	v_fma_f32 v201, v16, v204, v201
	v_fma_f32 v205, v17, v200, v205
	v_fma_f32 v238, v152, v239, v238
	v_fma_f32 v242, v152, v243, v242
	v_fma_f32 v238, v36, v243, v238
	v_fma_f32 v242, v37, v239, v242
	v_cvt_pk_bf16_f32 v135, v201, v205
	v_cvt_pk_bf16_f32 v187, v238, v242
	ds_write_b32 v103, v135 offset:12144
	ds_write_b32 v103, v187 offset:16768
	v_fma_f32 v206, v150, v201, v206
	v_fma_f32 v210, v150, v205, v210
	v_fma_f32 v206, v16, v205, v206
	v_fma_f32 v210, v17, v201, v210
	v_fma_f32 v233, v152, v238, v233
	v_fma_f32 v237, v152, v242, v237
	v_fma_f32 v233, v36, v242, v233
	v_fma_f32 v237, v37, v238, v237
	v_cvt_pk_bf16_f32 v128, v206, v210
	v_cvt_pk_bf16_f32 v136, v233, v237
	ds_write_b32 v103, v128 offset:12416
	ds_write_b32 v103, v136 offset:16496
	v_fma_f32 v207, v150, v206, v207
	v_fma_f32 v211, v150, v210, v211
	v_fma_f32 v207, v16, v210, v207
	v_fma_f32 v211, v17, v206, v211
	v_fma_f32 v232, v152, v233, v232
	v_fma_f32 v236, v152, v237, v236
	v_fma_f32 v232, v36, v237, v232
	v_fma_f32 v236, v37, v233, v236
	v_cvt_pk_bf16_f32 v131, v207, v211
	v_cvt_pk_bf16_f32 v139, v232, v236
	ds_write_b32 v103, v131 offset:12688
	ds_write_b32 v103, v139 offset:16224
	v_fma_f32 v208, v150, v207, v208
	v_fma_f32 v212, v150, v211, v212
	v_fma_f32 v208, v16, v211, v208
	v_fma_f32 v212, v17, v207, v212
	v_fma_f32 v231, v152, v232, v231
	v_fma_f32 v235, v152, v236, v235
	v_fma_f32 v231, v36, v236, v231
	v_fma_f32 v235, v37, v232, v235
	v_cvt_pk_bf16_f32 v132, v208, v212
	v_cvt_pk_bf16_f32 v143, v231, v235
	ds_write_b32 v103, v132 offset:12960
	ds_write_b32 v103, v143 offset:15952
	v_fma_f32 v209, v150, v208, v209
	v_fma_f32 v213, v150, v212, v213
	v_fma_f32 v209, v16, v212, v209
	v_fma_f32 v213, v17, v208, v213
	v_fma_f32 v230, v152, v231, v230
	v_fma_f32 v234, v152, v235, v234
	v_fma_f32 v230, v36, v235, v230
	v_fma_f32 v234, v37, v231, v234
	v_cvt_pk_bf16_f32 v135, v209, v213
	v_cvt_pk_bf16_f32 v187, v230, v234
	ds_write_b32 v103, v135 offset:13232
	ds_write_b32 v103, v187 offset:15680
	v_fma_f32 v214, v150, v209, v214
	v_fma_f32 v218, v150, v213, v218
	v_fma_f32 v214, v16, v213, v214
	v_fma_f32 v218, v17, v209, v218
	v_fma_f32 v225, v152, v230, v225
	v_fma_f32 v229, v152, v234, v229
	v_fma_f32 v225, v36, v234, v225
	v_fma_f32 v229, v37, v230, v229
	v_cvt_pk_bf16_f32 v128, v214, v218
; #define LAS __attribute__((address_space(3)))
; __device__ __forceinline__ unsigned pk2(float lo, float hi) { f32x2 v = {lo, hi}; nbf2 r = __builtin_convertvector(v, nbf2); return __builtin_bit_cast(unsigned, r); }
; #define WAVE_LDS_FENCE() asm volatile("s_waitcnt lgkmcnt(0)" ::: "memory")
; __device__ __forceinline__ float bf_at(const u32x4& lo, const u32x4& hi, int r) { const unsigned w = (r < 8 ? lo : hi)[(r & 7) >> 1]; return (r & 1) ? bf_hi(w) : bf_lo(w); }
; __device__ __forceinline__ void s5_out_phase(LAS unsigned char* lds, const bf16_t* UZ, const unsigned char* ws, const float* dskip, bf16_t* YG) {
;     ...
; #pragma unroll
;             for (int rr = 0; rr < 16; ++rr) {
;                 const int r = rr, rb = 15 - rr;
;                 { const f32x2 bb = {bf_at(fre0, fre1, r), bf_at(fim0, fim1, r)};
;                   const f32x2 n2 = cmac((f32x2){xfr, xfi}, (f32x2){ap[0].x, ap[0].x}, (f32x2){-ap[0].y, ap[0].y}, bb); xfr = n2.x; xfi = n2.y;
;                   *(LAS unsigned*)(xf + r * XB_PITCH + lane * 4) = pk2(n2.x, n2.y); }
;                 { const f32x2 bb = {bf_at(bre0, bre1, rb), bf_at(bim0, bim1, rb)};
;                   const f32x2 n2 = cmac((f32x2){xbr, xbi}, (f32x2){ap[1].x, ap[1].x}, (f32x2){-ap[1].y, ap[1].y}, bb); xbr = n2.x; xbi = n2.y;
;                   *(LAS unsigned*)(xbk + rb * XB_PITCH + lane * 4) = pk2(n2.x, n2.y); }
;             }
;             WAVE_LDS_FENCE();
; #pragma unroll
;             for (int ks = 0; ks < 4; ++ks) {
;                 const bf16x8 Xf = *(const LAS bf16x8*)(xf + fr * XB_PITCH + (8 * fq + 32 * ks) * 2);
;                 const bf16x8 Xb = *(const LAS bf16x8*)(xbk + fr * XB_PITCH + (8 * fq + 32 * ks) * 2);
;                 accY[mf] = __builtin_amdgcn_mfma_f32_16x16x32_bf16(Cf[0][ks], Xf, accY[mf], 0, 0, 0);
;                 accY[mb] = __builtin_amdgcn_mfma_f32_16x16x32_bf16(Cf[1][ks], Xb, accY[mb], 0, 0, 0);
;             }
	v_cvt_pk_bf16_f32 v136, v225, v229
	ds_write_b32 v103, v128 offset:13504
	ds_write_b32 v103, v136 offset:15408
	v_fma_f32 v215, v150, v214, v215
	v_fma_f32 v219, v150, v218, v219
	v_fma_f32 v215, v16, v218, v215
	v_fma_f32 v219, v17, v214, v219
	v_fma_f32 v224, v152, v225, v224
	v_fma_f32 v228, v152, v229, v228
	v_fma_f32 v224, v36, v229, v224
	v_fma_f32 v228, v37, v225, v228
	v_cvt_pk_bf16_f32 v131, v215, v219
	v_cvt_pk_bf16_f32 v139, v224, v228
	ds_write_b32 v103, v131 offset:13776
	ds_write_b32 v103, v139 offset:15136
	v_fma_f32 v216, v150, v215, v216
	v_fma_f32 v220, v150, v219, v220
	v_fma_f32 v216, v16, v219, v216
	v_fma_f32 v220, v17, v215, v220
	v_fma_f32 v223, v152, v224, v223
	v_fma_f32 v227, v152, v228, v227
	v_fma_f32 v223, v36, v228, v223
	v_fma_f32 v227, v37, v224, v227
	v_cvt_pk_bf16_f32 v132, v216, v220
	v_cvt_pk_bf16_f32 v143, v223, v227
	ds_write_b32 v103, v132 offset:14048
	ds_write_b32 v103, v143 offset:14864
	v_fma_f32 v217, v150, v216, v217
	v_fma_f32 v221, v150, v220, v221
	v_fma_f32 v217, v16, v220, v217
	v_fma_f32 v221, v17, v216, v221
	v_fma_f32 v222, v152, v223, v222
	v_fma_f32 v226, v152, v227, v226
	v_fma_f32 v222, v36, v227, v222
	v_fma_f32 v226, v37, v223, v226
	v_cvt_pk_bf16_f32 v135, v217, v221
	v_cvt_pk_bf16_f32 v187, v222, v226
	ds_write_b32 v103, v135 offset:14320
	ds_write_b32 v103, v187 offset:14592
	v_mov_b32_e32 v114, v217
	v_mov_b32_e32 v119, v221
	v_mov_b32_e32 v121, v222
	v_mov_b32_e32 v127, v226
	ds_read_b128 v[188:191], v110 offset:10240
	ds_read_b128 v[194:197], v110 offset:10304
	ds_read_b128 v[198:201], v110 offset:10368
	ds_read_b128 v[202:205], v110 offset:10432
	ds_read_b128 v[206:209], v110 offset:14592
	ds_read_b128 v[210:213], v110 offset:14656
	ds_read_b128 v[214:217], v110 offset:14720
	ds_read_b128 v[218:221], v110 offset:14784
	s_waitcnt lgkmcnt(7)
	v_mfma_f32_16x16x32_bf16 v[56:59], v[0:3], v[188:191], 0
	s_waitcnt lgkmcnt(3)
	v_mfma_f32_16x16x32_bf16 v[52:55], v[20:23], v[206:209], 0
	v_mfma_f32_16x16x32_bf16 v[56:59], v[4:7], v[194:197], v[56:59]
	s_waitcnt lgkmcnt(2)
	v_mfma_f32_16x16x32_bf16 v[52:55], v[24:27], v[210:213], v[52:55]
	v_mfma_f32_16x16x32_bf16 v[56:59], v[8:11], v[198:201], v[56:59]
	s_waitcnt lgkmcnt(1)
	v_mfma_f32_16x16x32_bf16 v[52:55], v[28:31], v[214:217], v[52:55]
	v_mfma_f32_16x16x32_bf16 v[56:59], v[12:15], v[202:205], v[56:59]
	s_waitcnt lgkmcnt(0)
	v_mfma_f32_16x16x32_bf16 v[52:55], v[32:35], v[218:221], v[52:55]
	v_mfma_f32_4x4x4_16b_bf16 v[188:191], v[168:169], v[60:61], 0 cbsz:4 abid:0
	v_mfma_f32_4x4x4_16b_bf16 v[194:197], v[168:169], v[68:69], 0 cbsz:4 abid:0
	v_mfma_f32_4x4x4_16b_bf16 v[198:201], v[168:169], v[60:61], 0 cbsz:4 abid:1
	v_mfma_f32_4x4x4_16b_bf16 v[202:205], v[168:169], v[68:69], 0 cbsz:4 abid:1
	v_mfma_f32_4x4x4_16b_bf16 v[206:209], v[168:169], v[60:61], 0 cbsz:4 abid:2
	v_mfma_f32_4x4x4_16b_bf16 v[210:213], v[168:169], v[68:69], 0 cbsz:4 abid:2
	v_mfma_f32_4x4x4_16b_bf16 v[214:217], v[168:169], v[60:61], 0 cbsz:4 abid:3
	v_mfma_f32_4x4x4_16b_bf16 v[218:221], v[168:169], v[68:69], 0 cbsz:4 abid:3
	v_mfma_f32_4x4x4_16b_bf16 v[222:225], v[170:171], v[76:77], 0 cbsz:4 abid:0
	v_mfma_f32_4x4x4_16b_bf16 v[226:229], v[170:171], v[84:85], 0 cbsz:4 abid:0
	v_mfma_f32_4x4x4_16b_bf16 v[230:233], v[170:171], v[76:77], 0 cbsz:4 abid:1
	v_mfma_f32_4x4x4_16b_bf16 v[234:237], v[170:171], v[84:85], 0 cbsz:4 abid:1
	v_mfma_f32_4x4x4_16b_bf16 v[238:241], v[170:171], v[76:77], 0 cbsz:4 abid:2
	v_mfma_f32_4x4x4_16b_bf16 v[242:245], v[170:171], v[84:85], 0 cbsz:4 abid:2
	v_mfma_f32_4x4x4_16b_bf16 v[246:249], v[170:171], v[76:77], 0 cbsz:4 abid:3
	v_mfma_f32_4x4x4_16b_bf16 v[250:253], v[170:171], v[84:85], 0 cbsz:4 abid:3
	v_mfma_f32_4x4x4_16b_bf16 v[188:191], v[168:169], v[62:63], v[188:191] cbsz:4 abid:4
	v_mfma_f32_4x4x4_16b_bf16 v[194:197], v[168:169], v[70:71], v[194:197] cbsz:4 abid:4
	v_mfma_f32_4x4x4_16b_bf16 v[198:201], v[168:169], v[62:63], v[198:201] cbsz:4 abid:5
	v_mfma_f32_4x4x4_16b_bf16 v[202:205], v[168:169], v[70:71], v[202:205] cbsz:4 abid:5
	v_mfma_f32_4x4x4_16b_bf16 v[206:209], v[168:169], v[62:63], v[206:209] cbsz:4 abid:6
	v_mfma_f32_4x4x4_16b_bf16 v[210:213], v[168:169], v[70:71], v[210:213] cbsz:4 abid:6
	v_mfma_f32_4x4x4_16b_bf16 v[214:217], v[168:169], v[62:63], v[214:217] cbsz:4 abid:7
	v_mfma_f32_4x4x4_16b_bf16 v[218:221], v[168:169], v[70:71], v[218:221] cbsz:4 abid:7
	v_mfma_f32_4x4x4_16b_bf16 v[222:225], v[170:171], v[78:79], v[222:225] cbsz:4 abid:4
	v_mfma_f32_4x4x4_16b_bf16 v[226:229], v[170:171], v[86:87], v[226:229] cbsz:4 abid:4
	v_mfma_f32_4x4x4_16b_bf16 v[230:233], v[170:171], v[78:79], v[230:233] cbsz:4 abid:5
	v_mfma_f32_4x4x4_16b_bf16 v[234:237], v[170:171], v[86:87], v[234:237] cbsz:4 abid:5
	v_mfma_f32_4x4x4_16b_bf16 v[238:241], v[170:171], v[78:79], v[238:241] cbsz:4 abid:6
	v_mfma_f32_4x4x4_16b_bf16 v[242:245], v[170:171], v[86:87], v[242:245] cbsz:4 abid:6
	v_mfma_f32_4x4x4_16b_bf16 v[246:249], v[170:171], v[78:79], v[246:249] cbsz:4 abid:7
	v_mfma_f32_4x4x4_16b_bf16 v[250:253], v[170:171], v[86:87], v[250:253] cbsz:4 abid:7
	v_mfma_f32_4x4x4_16b_bf16 v[188:191], v[168:169], v[64:65], v[188:191] cbsz:4 abid:8
	v_mfma_f32_4x4x4_16b_bf16 v[194:197], v[168:169], v[72:73], v[194:197] cbsz:4 abid:8
	v_mfma_f32_4x4x4_16b_bf16 v[198:201], v[168:169], v[64:65], v[198:201] cbsz:4 abid:9
	v_mfma_f32_4x4x4_16b_bf16 v[202:205], v[168:169], v[72:73], v[202:205] cbsz:4 abid:9
	v_mfma_f32_4x4x4_16b_bf16 v[206:209], v[168:169], v[64:65], v[206:209] cbsz:4 abid:10
	v_mfma_f32_4x4x4_16b_bf16 v[210:213], v[168:169], v[72:73], v[210:213] cbsz:4 abid:10
	v_mfma_f32_4x4x4_16b_bf16 v[214:217], v[168:169], v[64:65], v[214:217] cbsz:4 abid:11
; #define LAS __attribute__((address_space(3)))
; #define WAVE_LDS_FENCE() asm volatile("s_waitcnt lgkmcnt(0)" ::: "memory")
; __device__ __forceinline__ void s5_out_phase(LAS unsigned char* lds, const bf16_t* UZ, const unsigned char* ws, const float* dskip, bf16_t* YG) {
;     ...
;         for (int mm = 0; mm < 4; ++mm) {
;             const int mf = mm, mb = 3 - mm;
; #pragma unroll
;             for (int nt = 0; nt < 8; ++nt) {
;                 const f32x4 z = {0.f, 0.f, 0.f, 0.f};
;                 const f32x4 cf = __builtin_amdgcn_mfma_f32_16x16x16bf16_1k(Uf[mf], Bf[0][nt], z, 0, 0, 0);
;                 const f32x4 cb = __builtin_amdgcn_mfma_f32_16x16x16bf16_1k(Uf[mb], Bf[1][nt], z, 0, 0, 0);
;                 u32x2 wf, wb; wf.x = pk2(cf[0], cf[1]); wf.y = pk2(cf[2], cf[3]); wb.x = pk2(cb[0], cb[1]); wb.y = pk2(cb[2], cb[3]);
;                 *(LAS u32x2*)(wl + nt * 640 + wofs) = wf;
;                 *(LAS u32x2*)(wl + BUT_BYTES + nt * 640 + wofs) = wb;
;             }
;             WAVE_LDS_FENCE();
;             const LAS unsigned char* rp = wl + lane * 80;
;             const u32x4 fre0 = *(const LAS u32x4*)(rp), fre1 = *(const LAS u32x4*)(rp + 16), fim0 = *(const LAS u32x4*)(rp + 32), fim1 = *(const LAS u32x4*)(rp + 48);
;             const u32x4 bre0 = *(const LAS u32x4*)(rp + BUT_BYTES), bre1 = *(const LAS u32x4*)(rp + BUT_BYTES + 16), bim0 = *(const LAS u32x4*)(rp + BUT_BYTES + 32), bim1 = *(const LAS u32x4*)(rp + BUT_BYTES + 48);
;             LAS unsigned char* xf = wl + 2 * BUT_BYTES; LAS unsigned char* xbk = xf + XB_BYTES;
; #pragma unroll
;             for (int rr = 0; rr < 16; ++rr) {
;                 const int r = rr, rb = 15 - rr;
;                 { const f32x2 bb = {bf_at(fre0, fre1, r), bf_at(fim0, fim1, r)};
;                   const f32x2 n2 = cmac((f32x2){xfr, xfi}, (f32x2){ap[0].x, ap[0].x}, (f32x2){-ap[0].y, ap[0].y}, bb); xfr = n2.x; xfi = n2.y;
;                   *(LAS unsigned*)(xf + r * XB_PITCH + lane * 4) = pk2(n2.x, n2.y); }
;                 { const f32x2 bb = {bf_at(bre0, bre1, rb), bf_at(bim0, bim1, rb)};
;                   const f32x2 n2 = cmac((f32x2){xbr, xbi}, (f32x2){ap[1].x, ap[1].x}, (f32x2){-ap[1].y, ap[1].y}, bb); xbr = n2.x; xbi = n2.y;
;                   *(LAS unsigned*)(xbk + rb * XB_PITCH + lane * 4) = pk2(n2.x, n2.y); }
;             }
	v_mfma_f32_4x4x4_16b_bf16 v[218:221], v[168:169], v[72:73], v[218:221] cbsz:4 abid:11
	v_mfma_f32_4x4x4_16b_bf16 v[222:225], v[170:171], v[80:81], v[222:225] cbsz:4 abid:8
	v_mfma_f32_4x4x4_16b_bf16 v[226:229], v[170:171], v[88:89], v[226:229] cbsz:4 abid:8
	v_mfma_f32_4x4x4_16b_bf16 v[230:233], v[170:171], v[80:81], v[230:233] cbsz:4 abid:9
	v_mfma_f32_4x4x4_16b_bf16 v[234:237], v[170:171], v[88:89], v[234:237] cbsz:4 abid:9
	v_mfma_f32_4x4x4_16b_bf16 v[238:241], v[170:171], v[80:81], v[238:241] cbsz:4 abid:10
	v_mfma_f32_4x4x4_16b_bf16 v[242:245], v[170:171], v[88:89], v[242:245] cbsz:4 abid:10
	v_mfma_f32_4x4x4_16b_bf16 v[246:249], v[170:171], v[80:81], v[246:249] cbsz:4 abid:11
	v_mfma_f32_4x4x4_16b_bf16 v[250:253], v[170:171], v[88:89], v[250:253] cbsz:4 abid:11
	v_mfma_f32_4x4x4_16b_bf16 v[188:191], v[168:169], v[66:67], v[188:191] cbsz:4 abid:12
	v_mfma_f32_4x4x4_16b_bf16 v[194:197], v[168:169], v[74:75], v[194:197] cbsz:4 abid:12
	v_mfma_f32_4x4x4_16b_bf16 v[198:201], v[168:169], v[66:67], v[198:201] cbsz:4 abid:13
	v_mfma_f32_4x4x4_16b_bf16 v[202:205], v[168:169], v[74:75], v[202:205] cbsz:4 abid:13
	v_mfma_f32_4x4x4_16b_bf16 v[206:209], v[168:169], v[66:67], v[206:209] cbsz:4 abid:14
	v_mfma_f32_4x4x4_16b_bf16 v[210:213], v[168:169], v[74:75], v[210:213] cbsz:4 abid:14
	v_mfma_f32_4x4x4_16b_bf16 v[214:217], v[168:169], v[66:67], v[214:217] cbsz:4 abid:15
	v_mfma_f32_4x4x4_16b_bf16 v[218:221], v[168:169], v[74:75], v[218:221] cbsz:4 abid:15
	v_mfma_f32_4x4x4_16b_bf16 v[222:225], v[170:171], v[82:83], v[222:225] cbsz:4 abid:12
	v_mfma_f32_4x4x4_16b_bf16 v[226:229], v[170:171], v[90:91], v[226:229] cbsz:4 abid:12
	v_mfma_f32_4x4x4_16b_bf16 v[230:233], v[170:171], v[82:83], v[230:233] cbsz:4 abid:13
	v_mfma_f32_4x4x4_16b_bf16 v[234:237], v[170:171], v[90:91], v[234:237] cbsz:4 abid:13
	v_mfma_f32_4x4x4_16b_bf16 v[238:241], v[170:171], v[82:83], v[238:241] cbsz:4 abid:14
	v_mfma_f32_4x4x4_16b_bf16 v[242:245], v[170:171], v[90:91], v[242:245] cbsz:4 abid:14
	v_mfma_f32_4x4x4_16b_bf16 v[246:249], v[170:171], v[82:83], v[246:249] cbsz:4 abid:15
	v_mfma_f32_4x4x4_16b_bf16 v[250:253], v[170:171], v[90:91], v[250:253] cbsz:4 abid:15
	v_fma_f32 v188, v150, v114, v188
	v_fma_f32 v194, v150, v119, v194
	v_fma_f32 v188, v16, v119, v188
	v_fma_f32 v194, v17, v114, v194
	v_fma_f32 v249, v152, v121, v249
	v_fma_f32 v253, v152, v127, v253
	v_fma_f32 v249, v36, v127, v249
	v_fma_f32 v253, v37, v121, v253
	v_cvt_pk_bf16_f32 v128, v188, v194
	v_cvt_pk_bf16_f32 v136, v249, v253
	ds_write_b32 v103, v128 offset:10240
	ds_write_b32 v103, v136 offset:18672
	v_fma_f32 v189, v150, v188, v189
	v_fma_f32 v195, v150, v194, v195
	v_fma_f32 v189, v16, v194, v189
	v_fma_f32 v195, v17, v188, v195
	v_fma_f32 v248, v152, v249, v248
	v_fma_f32 v252, v152, v253, v252
	v_fma_f32 v248, v36, v253, v248
	v_fma_f32 v252, v37, v249, v252
	v_cvt_pk_bf16_f32 v131, v189, v195
	v_cvt_pk_bf16_f32 v139, v248, v252
	ds_write_b32 v103, v131 offset:10512
	ds_write_b32 v103, v139 offset:18400
	v_fma_f32 v190, v150, v189, v190
	v_fma_f32 v196, v150, v195, v196
	v_fma_f32 v190, v16, v195, v190
	v_fma_f32 v196, v17, v189, v196
	v_fma_f32 v247, v152, v248, v247
	v_fma_f32 v251, v152, v252, v251
	v_fma_f32 v247, v36, v252, v247
	v_fma_f32 v251, v37, v248, v251
	v_cvt_pk_bf16_f32 v132, v190, v196
	v_cvt_pk_bf16_f32 v143, v247, v251
	ds_write_b32 v103, v132 offset:10784
	ds_write_b32 v103, v143 offset:18128
	v_fma_f32 v191, v150, v190, v191
	v_fma_f32 v197, v150, v196, v197
	v_fma_f32 v191, v16, v196, v191
	v_fma_f32 v197, v17, v190, v197
	v_fma_f32 v246, v152, v247, v246
	v_fma_f32 v250, v152, v251, v250
	v_fma_f32 v246, v36, v251, v246
	v_fma_f32 v250, v37, v247, v250
	v_cvt_pk_bf16_f32 v135, v191, v197
	v_cvt_pk_bf16_f32 v187, v246, v250
	ds_write_b32 v103, v135 offset:11056
	ds_write_b32 v103, v187 offset:17856
	v_fma_f32 v198, v150, v191, v198
	v_fma_f32 v202, v150, v197, v202
	v_fma_f32 v198, v16, v197, v198
	v_fma_f32 v202, v17, v191, v202
	v_fma_f32 v241, v152, v246, v241
	v_fma_f32 v245, v152, v250, v245
	v_fma_f32 v241, v36, v250, v241
	v_fma_f32 v245, v37, v246, v245
	v_cvt_pk_bf16_f32 v128, v198, v202
	v_cvt_pk_bf16_f32 v136, v241, v245
	ds_write_b32 v103, v128 offset:11328
	ds_write_b32 v103, v136 offset:17584
	v_fma_f32 v199, v150, v198, v199
	v_fma_f32 v203, v150, v202, v203
	v_fma_f32 v199, v16, v202, v199
	v_fma_f32 v203, v17, v198, v203
	v_fma_f32 v240, v152, v241, v240
	v_fma_f32 v244, v152, v245, v244
	v_fma_f32 v240, v36, v245, v240
	v_fma_f32 v244, v37, v241, v244
	v_cvt_pk_bf16_f32 v131, v199, v203
	v_cvt_pk_bf16_f32 v139, v240, v244
	ds_write_b32 v103, v131 offset:11600
	ds_write_b32 v103, v139 offset:17312
	v_fma_f32 v200, v150, v199, v200
	v_fma_f32 v204, v150, v203, v204
	v_fma_f32 v200, v16, v203, v200
	v_fma_f32 v204, v17, v199, v204
	v_fma_f32 v239, v152, v240, v239
	v_fma_f32 v243, v152, v244, v243
	v_fma_f32 v239, v36, v244, v239
	v_fma_f32 v243, v37, v240, v243
	v_cvt_pk_bf16_f32 v132, v200, v204
	v_cvt_pk_bf16_f32 v143, v239, v243
	ds_write_b32 v103, v132 offset:11872
	ds_write_b32 v103, v143 offset:17040
	v_fma_f32 v201, v150, v200, v201
	v_fma_f32 v205, v150, v204, v205
	v_fma_f32 v201, v16, v204, v201
	v_fma_f32 v205, v17, v200, v205
	v_fma_f32 v238, v152, v239, v238
	v_fma_f32 v242, v152, v243, v242
	v_fma_f32 v238, v36, v243, v238
	v_fma_f32 v242, v37, v239, v242
	v_cvt_pk_bf16_f32 v135, v201, v205
	v_cvt_pk_bf16_f32 v187, v238, v242
	ds_write_b32 v103, v135 offset:12144
	ds_write_b32 v103, v187 offset:16768
	v_fma_f32 v206, v150, v201, v206
	v_fma_f32 v210, v150, v205, v210
	v_fma_f32 v206, v16, v205, v206
	v_fma_f32 v210, v17, v201, v210
; #define LAS __attribute__((address_space(3)))
; __device__ __forceinline__ unsigned pk2(float lo, float hi) { f32x2 v = {lo, hi}; nbf2 r = __builtin_convertvector(v, nbf2); return __builtin_bit_cast(unsigned, r); }
; __device__ __forceinline__ void s5_out_phase(LAS unsigned char* lds, const bf16_t* UZ, const unsigned char* ws, const float* dskip, bf16_t* YG) {
;     ...
;         for (int mm = 0; mm < 4; ++mm) {
;             const int mf = mm, mb = 3 - mm;
; #pragma unroll
;             for (int nt = 0; nt < 8; ++nt) {
;                 const f32x4 z = {0.f, 0.f, 0.f, 0.f};
;                 const f32x4 cf = __builtin_amdgcn_mfma_f32_16x16x16bf16_1k(Uf[mf], Bf[0][nt], z, 0, 0, 0);
;                 const f32x4 cb = __builtin_amdgcn_mfma_f32_16x16x16bf16_1k(Uf[mb], Bf[1][nt], z, 0, 0, 0);
;                 u32x2 wf, wb; wf.x = pk2(cf[0], cf[1]); wf.y = pk2(cf[2], cf[3]); wb.x = pk2(cb[0], cb[1]); wb.y = pk2(cb[2], cb[3]);
;                 *(LAS u32x2*)(wl + nt * 640 + wofs) = wf;
;                 *(LAS u32x2*)(wl + BUT_BYTES + nt * 640 + wofs) = wb;
;     ...
; #pragma unroll
;             for (int rr = 0; rr < 16; ++rr) {
;                 const int r = rr, rb = 15 - rr;
;                 { const f32x2 bb = {bf_at(fre0, fre1, r), bf_at(fim0, fim1, r)};
;                   const f32x2 n2 = cmac((f32x2){xfr, xfi}, (f32x2){ap[0].x, ap[0].x}, (f32x2){-ap[0].y, ap[0].y}, bb); xfr = n2.x; xfi = n2.y;
;                   *(LAS unsigned*)(xf + r * XB_PITCH + lane * 4) = pk2(n2.x, n2.y); }
;                 { const f32x2 bb = {bf_at(bre0, bre1, rb), bf_at(bim0, bim1, rb)};
;                   const f32x2 n2 = cmac((f32x2){xbr, xbi}, (f32x2){ap[1].x, ap[1].x}, (f32x2){-ap[1].y, ap[1].y}, bb); xbr = n2.x; xbi = n2.y;
;                   *(LAS unsigned*)(xbk + rb * XB_PITCH + lane * 4) = pk2(n2.x, n2.y); }
;             }
;             WAVE_LDS_FENCE();
; #pragma unroll
;             for (int ks = 0; ks < 4; ++ks) {
;                 const bf16x8 Xf = *(const LAS bf16x8*)(xf + fr * XB_PITCH + (8 * fq + 32 * ks) * 2);
;                 const bf16x8 Xb = *(const LAS bf16x8*)(xbk + fr * XB_PITCH + (8 * fq + 32 * ks) * 2);
;                 accY[mf] = __builtin_amdgcn_mfma_f32_16x16x32_bf16(Cf[0][ks], Xf, accY[mf], 0, 0, 0);
;                 accY[mb] = __builtin_amdgcn_mfma_f32_16x16x32_bf16(Cf[1][ks], Xb, accY[mb], 0, 0, 0);
;             }
	v_fma_f32 v233, v152, v238, v233
	v_fma_f32 v237, v152, v242, v237
	v_fma_f32 v233, v36, v242, v233
	v_fma_f32 v237, v37, v238, v237
	v_cvt_pk_bf16_f32 v128, v206, v210
	v_cvt_pk_bf16_f32 v136, v233, v237
	ds_write_b32 v103, v128 offset:12416
	ds_write_b32 v103, v136 offset:16496
	v_fma_f32 v207, v150, v206, v207
	v_fma_f32 v211, v150, v210, v211
	v_fma_f32 v207, v16, v210, v207
	v_fma_f32 v211, v17, v206, v211
	v_fma_f32 v232, v152, v233, v232
	v_fma_f32 v236, v152, v237, v236
	v_fma_f32 v232, v36, v237, v232
	v_fma_f32 v236, v37, v233, v236
	v_cvt_pk_bf16_f32 v131, v207, v211
	v_cvt_pk_bf16_f32 v139, v232, v236
	ds_write_b32 v103, v131 offset:12688
	ds_write_b32 v103, v139 offset:16224
	v_fma_f32 v208, v150, v207, v208
	v_fma_f32 v212, v150, v211, v212
	v_fma_f32 v208, v16, v211, v208
	v_fma_f32 v212, v17, v207, v212
	v_fma_f32 v231, v152, v232, v231
	v_fma_f32 v235, v152, v236, v235
	v_fma_f32 v231, v36, v236, v231
	v_fma_f32 v235, v37, v232, v235
	v_cvt_pk_bf16_f32 v132, v208, v212
	v_cvt_pk_bf16_f32 v143, v231, v235
	ds_write_b32 v103, v132 offset:12960
	ds_write_b32 v103, v143 offset:15952
	v_fma_f32 v209, v150, v208, v209
	v_fma_f32 v213, v150, v212, v213
	v_fma_f32 v209, v16, v212, v209
	v_fma_f32 v213, v17, v208, v213
	v_fma_f32 v230, v152, v231, v230
	v_fma_f32 v234, v152, v235, v234
	v_fma_f32 v230, v36, v235, v230
	v_fma_f32 v234, v37, v231, v234
	v_cvt_pk_bf16_f32 v135, v209, v213
	v_cvt_pk_bf16_f32 v187, v230, v234
	ds_write_b32 v103, v135 offset:13232
	ds_write_b32 v103, v187 offset:15680
	v_fma_f32 v214, v150, v209, v214
	v_fma_f32 v218, v150, v213, v218
	v_fma_f32 v214, v16, v213, v214
	v_fma_f32 v218, v17, v209, v218
	v_fma_f32 v225, v152, v230, v225
	v_fma_f32 v229, v152, v234, v229
	v_fma_f32 v225, v36, v234, v225
	v_fma_f32 v229, v37, v230, v229
	v_cvt_pk_bf16_f32 v128, v214, v218
	v_cvt_pk_bf16_f32 v136, v225, v229
	ds_write_b32 v103, v128 offset:13504
	ds_write_b32 v103, v136 offset:15408
	v_fma_f32 v215, v150, v214, v215
	v_fma_f32 v219, v150, v218, v219
	v_fma_f32 v215, v16, v218, v215
	v_fma_f32 v219, v17, v214, v219
	v_fma_f32 v224, v152, v225, v224
	v_fma_f32 v228, v152, v229, v228
	v_fma_f32 v224, v36, v229, v224
	v_fma_f32 v228, v37, v225, v228
	v_cvt_pk_bf16_f32 v131, v215, v219
	v_cvt_pk_bf16_f32 v139, v224, v228
	ds_write_b32 v103, v131 offset:13776
	ds_write_b32 v103, v139 offset:15136
	v_fma_f32 v216, v150, v215, v216
	v_fma_f32 v220, v150, v219, v220
	v_fma_f32 v216, v16, v219, v216
	v_fma_f32 v220, v17, v215, v220
	v_fma_f32 v223, v152, v224, v223
	v_fma_f32 v227, v152, v228, v227
	v_fma_f32 v223, v36, v228, v223
	v_fma_f32 v227, v37, v224, v227
	v_cvt_pk_bf16_f32 v132, v216, v220
	v_cvt_pk_bf16_f32 v143, v223, v227
	ds_write_b32 v103, v132 offset:14048
	ds_write_b32 v103, v143 offset:14864
	v_fma_f32 v217, v150, v216, v217
	v_fma_f32 v221, v150, v220, v221
	v_fma_f32 v217, v16, v220, v217
	v_fma_f32 v221, v17, v216, v221
	v_fma_f32 v222, v152, v223, v222
	v_fma_f32 v226, v152, v227, v226
	v_fma_f32 v222, v36, v227, v222
	v_fma_f32 v226, v37, v223, v226
	v_cvt_pk_bf16_f32 v135, v217, v221
	v_cvt_pk_bf16_f32 v187, v222, v226
	ds_write_b32 v103, v135 offset:14320
	ds_write_b32 v103, v187 offset:14592
	v_mov_b32_e32 v114, v217
	v_mov_b32_e32 v119, v221
	v_mov_b32_e32 v121, v222
	v_mov_b32_e32 v127, v226
	ds_read_b128 v[188:191], v110 offset:10240
	ds_read_b128 v[194:197], v110 offset:10304
	ds_read_b128 v[198:201], v110 offset:10368
	ds_read_b128 v[202:205], v110 offset:10432
	ds_read_b128 v[206:209], v110 offset:14592
	ds_read_b128 v[210:213], v110 offset:14656
	ds_read_b128 v[214:217], v110 offset:14720
	ds_read_b128 v[218:221], v110 offset:14784
	s_waitcnt lgkmcnt(7)
	v_mfma_f32_16x16x32_bf16 v[52:55], v[0:3], v[188:191], v[52:55]
	s_waitcnt lgkmcnt(3)
	v_mfma_f32_16x16x32_bf16 v[56:59], v[20:23], v[206:209], v[56:59]
	v_mfma_f32_16x16x32_bf16 v[52:55], v[4:7], v[194:197], v[52:55]
	s_waitcnt lgkmcnt(2)
	v_mfma_f32_16x16x32_bf16 v[56:59], v[24:27], v[210:213], v[56:59]
	v_mfma_f32_16x16x32_bf16 v[52:55], v[8:11], v[198:201], v[52:55]
	s_waitcnt lgkmcnt(1)
	v_mfma_f32_16x16x32_bf16 v[56:59], v[28:31], v[214:217], v[56:59]
	v_mfma_f32_16x16x32_bf16 v[52:55], v[12:15], v[202:205], v[52:55]
	s_waitcnt lgkmcnt(0)
	v_mfma_f32_16x16x32_bf16 v[56:59], v[32:35], v[218:221], v[56:59]
	v_mfma_f32_4x4x4_16b_bf16 v[188:191], v[116:117], v[60:61], 0 cbsz:4 abid:0
	v_mfma_f32_4x4x4_16b_bf16 v[194:197], v[116:117], v[68:69], 0 cbsz:4 abid:0
	v_mfma_f32_4x4x4_16b_bf16 v[198:201], v[116:117], v[60:61], 0 cbsz:4 abid:1
	v_mfma_f32_4x4x4_16b_bf16 v[202:205], v[116:117], v[68:69], 0 cbsz:4 abid:1
	v_mfma_f32_4x4x4_16b_bf16 v[206:209], v[116:117], v[60:61], 0 cbsz:4 abid:2
	v_mfma_f32_4x4x4_16b_bf16 v[210:213], v[116:117], v[68:69], 0 cbsz:4 abid:2
	v_mfma_f32_4x4x4_16b_bf16 v[214:217], v[116:117], v[60:61], 0 cbsz:4 abid:3
	v_mfma_f32_4x4x4_16b_bf16 v[218:221], v[116:117], v[68:69], 0 cbsz:4 abid:3
	v_mfma_f32_4x4x4_16b_bf16 v[222:225], v[172:173], v[76:77], 0 cbsz:4 abid:0
	v_mfma_f32_4x4x4_16b_bf16 v[226:229], v[172:173], v[84:85], 0 cbsz:4 abid:0
	v_mfma_f32_4x4x4_16b_bf16 v[230:233], v[172:173], v[76:77], 0 cbsz:4 abid:1
	v_mfma_f32_4x4x4_16b_bf16 v[234:237], v[172:173], v[84:85], 0 cbsz:4 abid:1
	v_mfma_f32_4x4x4_16b_bf16 v[238:241], v[172:173], v[76:77], 0 cbsz:4 abid:2
	v_mfma_f32_4x4x4_16b_bf16 v[242:245], v[172:173], v[84:85], 0 cbsz:4 abid:2
	v_mfma_f32_4x4x4_16b_bf16 v[246:249], v[172:173], v[76:77], 0 cbsz:4 abid:3
	v_mfma_f32_4x4x4_16b_bf16 v[250:253], v[172:173], v[84:85], 0 cbsz:4 abid:3
	v_mfma_f32_4x4x4_16b_bf16 v[188:191], v[116:117], v[62:63], v[188:191] cbsz:4 abid:4
; #define LAS __attribute__((address_space(3)))
; #define WAVE_LDS_FENCE() asm volatile("s_waitcnt lgkmcnt(0)" ::: "memory")
; __device__ __forceinline__ void s5_out_phase(LAS unsigned char* lds, const bf16_t* UZ, const unsigned char* ws, const float* dskip, bf16_t* YG) {
;     ...
;         for (int mm = 0; mm < 4; ++mm) {
;             const int mf = mm, mb = 3 - mm;
; #pragma unroll
;             for (int nt = 0; nt < 8; ++nt) {
;                 const f32x4 z = {0.f, 0.f, 0.f, 0.f};
;                 const f32x4 cf = __builtin_amdgcn_mfma_f32_16x16x16bf16_1k(Uf[mf], Bf[0][nt], z, 0, 0, 0);
;                 const f32x4 cb = __builtin_amdgcn_mfma_f32_16x16x16bf16_1k(Uf[mb], Bf[1][nt], z, 0, 0, 0);
;                 u32x2 wf, wb; wf.x = pk2(cf[0], cf[1]); wf.y = pk2(cf[2], cf[3]); wb.x = pk2(cb[0], cb[1]); wb.y = pk2(cb[2], cb[3]);
;                 *(LAS u32x2*)(wl + nt * 640 + wofs) = wf;
;                 *(LAS u32x2*)(wl + BUT_BYTES + nt * 640 + wofs) = wb;
;             }
;             WAVE_LDS_FENCE();
;             const LAS unsigned char* rp = wl + lane * 80;
;             const u32x4 fre0 = *(const LAS u32x4*)(rp), fre1 = *(const LAS u32x4*)(rp + 16), fim0 = *(const LAS u32x4*)(rp + 32), fim1 = *(const LAS u32x4*)(rp + 48);
;             const u32x4 bre0 = *(const LAS u32x4*)(rp + BUT_BYTES), bre1 = *(const LAS u32x4*)(rp + BUT_BYTES + 16), bim0 = *(const LAS u32x4*)(rp + BUT_BYTES + 32), bim1 = *(const LAS u32x4*)(rp + BUT_BYTES + 48);
;             LAS unsigned char* xf = wl + 2 * BUT_BYTES; LAS unsigned char* xbk = xf + XB_BYTES;
; #pragma unroll
;             for (int rr = 0; rr < 16; ++rr) {
;                 const int r = rr, rb = 15 - rr;
;                 { const f32x2 bb = {bf_at(fre0, fre1, r), bf_at(fim0, fim1, r)};
;                   const f32x2 n2 = cmac((f32x2){xfr, xfi}, (f32x2){ap[0].x, ap[0].x}, (f32x2){-ap[0].y, ap[0].y}, bb); xfr = n2.x; xfi = n2.y;
;                   *(LAS unsigned*)(xf + r * XB_PITCH + lane * 4) = pk2(n2.x, n2.y); }
;                 { const f32x2 bb = {bf_at(bre0, bre1, rb), bf_at(bim0, bim1, rb)};
;                   const f32x2 n2 = cmac((f32x2){xbr, xbi}, (f32x2){ap[1].x, ap[1].x}, (f32x2){-ap[1].y, ap[1].y}, bb); xbr = n2.x; xbi = n2.y;
;                   *(LAS unsigned*)(xbk + rb * XB_PITCH + lane * 4) = pk2(n2.x, n2.y); }
;             }
	v_mfma_f32_4x4x4_16b_bf16 v[194:197], v[116:117], v[70:71], v[194:197] cbsz:4 abid:4
	v_mfma_f32_4x4x4_16b_bf16 v[198:201], v[116:117], v[62:63], v[198:201] cbsz:4 abid:5
	v_mfma_f32_4x4x4_16b_bf16 v[202:205], v[116:117], v[70:71], v[202:205] cbsz:4 abid:5
	v_mfma_f32_4x4x4_16b_bf16 v[206:209], v[116:117], v[62:63], v[206:209] cbsz:4 abid:6
	v_mfma_f32_4x4x4_16b_bf16 v[210:213], v[116:117], v[70:71], v[210:213] cbsz:4 abid:6
	v_mfma_f32_4x4x4_16b_bf16 v[214:217], v[116:117], v[62:63], v[214:217] cbsz:4 abid:7
	v_mfma_f32_4x4x4_16b_bf16 v[218:221], v[116:117], v[70:71], v[218:221] cbsz:4 abid:7
	v_mfma_f32_4x4x4_16b_bf16 v[222:225], v[172:173], v[78:79], v[222:225] cbsz:4 abid:4
	v_mfma_f32_4x4x4_16b_bf16 v[226:229], v[172:173], v[86:87], v[226:229] cbsz:4 abid:4
	v_mfma_f32_4x4x4_16b_bf16 v[230:233], v[172:173], v[78:79], v[230:233] cbsz:4 abid:5
	v_mfma_f32_4x4x4_16b_bf16 v[234:237], v[172:173], v[86:87], v[234:237] cbsz:4 abid:5
	v_mfma_f32_4x4x4_16b_bf16 v[238:241], v[172:173], v[78:79], v[238:241] cbsz:4 abid:6
	v_mfma_f32_4x4x4_16b_bf16 v[242:245], v[172:173], v[86:87], v[242:245] cbsz:4 abid:6
	v_mfma_f32_4x4x4_16b_bf16 v[246:249], v[172:173], v[78:79], v[246:249] cbsz:4 abid:7
	v_mfma_f32_4x4x4_16b_bf16 v[250:253], v[172:173], v[86:87], v[250:253] cbsz:4 abid:7
	v_mfma_f32_4x4x4_16b_bf16 v[188:191], v[116:117], v[64:65], v[188:191] cbsz:4 abid:8
	v_mfma_f32_4x4x4_16b_bf16 v[194:197], v[116:117], v[72:73], v[194:197] cbsz:4 abid:8
	v_mfma_f32_4x4x4_16b_bf16 v[198:201], v[116:117], v[64:65], v[198:201] cbsz:4 abid:9
	v_mfma_f32_4x4x4_16b_bf16 v[202:205], v[116:117], v[72:73], v[202:205] cbsz:4 abid:9
	v_mfma_f32_4x4x4_16b_bf16 v[206:209], v[116:117], v[64:65], v[206:209] cbsz:4 abid:10
	v_mfma_f32_4x4x4_16b_bf16 v[210:213], v[116:117], v[72:73], v[210:213] cbsz:4 abid:10
	v_mfma_f32_4x4x4_16b_bf16 v[214:217], v[116:117], v[64:65], v[214:217] cbsz:4 abid:11
	v_mfma_f32_4x4x4_16b_bf16 v[218:221], v[116:117], v[72:73], v[218:221] cbsz:4 abid:11
	v_mfma_f32_4x4x4_16b_bf16 v[222:225], v[172:173], v[80:81], v[222:225] cbsz:4 abid:8
	v_mfma_f32_4x4x4_16b_bf16 v[226:229], v[172:173], v[88:89], v[226:229] cbsz:4 abid:8
	v_mfma_f32_4x4x4_16b_bf16 v[230:233], v[172:173], v[80:81], v[230:233] cbsz:4 abid:9
	v_mfma_f32_4x4x4_16b_bf16 v[234:237], v[172:173], v[88:89], v[234:237] cbsz:4 abid:9
	v_mfma_f32_4x4x4_16b_bf16 v[238:241], v[172:173], v[80:81], v[238:241] cbsz:4 abid:10
	v_mfma_f32_4x4x4_16b_bf16 v[242:245], v[172:173], v[88:89], v[242:245] cbsz:4 abid:10
	v_mfma_f32_4x4x4_16b_bf16 v[246:249], v[172:173], v[80:81], v[246:249] cbsz:4 abid:11
	v_mfma_f32_4x4x4_16b_bf16 v[250:253], v[172:173], v[88:89], v[250:253] cbsz:4 abid:11
	v_mfma_f32_4x4x4_16b_bf16 v[188:191], v[116:117], v[66:67], v[188:191] cbsz:4 abid:12
	v_mfma_f32_4x4x4_16b_bf16 v[194:197], v[116:117], v[74:75], v[194:197] cbsz:4 abid:12
	v_mfma_f32_4x4x4_16b_bf16 v[198:201], v[116:117], v[66:67], v[198:201] cbsz:4 abid:13
	v_mfma_f32_4x4x4_16b_bf16 v[202:205], v[116:117], v[74:75], v[202:205] cbsz:4 abid:13
	v_mfma_f32_4x4x4_16b_bf16 v[206:209], v[116:117], v[66:67], v[206:209] cbsz:4 abid:14
	v_mfma_f32_4x4x4_16b_bf16 v[210:213], v[116:117], v[74:75], v[210:213] cbsz:4 abid:14
	v_mfma_f32_4x4x4_16b_bf16 v[214:217], v[116:117], v[66:67], v[214:217] cbsz:4 abid:15
	v_mfma_f32_4x4x4_16b_bf16 v[218:221], v[116:117], v[74:75], v[218:221] cbsz:4 abid:15
	v_mfma_f32_4x4x4_16b_bf16 v[222:225], v[172:173], v[82:83], v[222:225] cbsz:4 abid:12
	v_mfma_f32_4x4x4_16b_bf16 v[226:229], v[172:173], v[90:91], v[226:229] cbsz:4 abid:12
	v_mfma_f32_4x4x4_16b_bf16 v[230:233], v[172:173], v[82:83], v[230:233] cbsz:4 abid:13
	v_mfma_f32_4x4x4_16b_bf16 v[234:237], v[172:173], v[90:91], v[234:237] cbsz:4 abid:13
	v_mfma_f32_4x4x4_16b_bf16 v[238:241], v[172:173], v[82:83], v[238:241] cbsz:4 abid:14
	v_mfma_f32_4x4x4_16b_bf16 v[242:245], v[172:173], v[90:91], v[242:245] cbsz:4 abid:14
	v_mfma_f32_4x4x4_16b_bf16 v[246:249], v[172:173], v[82:83], v[246:249] cbsz:4 abid:15
	v_mfma_f32_4x4x4_16b_bf16 v[250:253], v[172:173], v[90:91], v[250:253] cbsz:4 abid:15
	v_fma_f32 v188, v150, v114, v188
	v_fma_f32 v194, v150, v119, v194
	v_fma_f32 v188, v16, v119, v188
	v_fma_f32 v194, v17, v114, v194
	v_fma_f32 v249, v152, v121, v249
	v_fma_f32 v253, v152, v127, v253
	v_fma_f32 v249, v36, v127, v249
	v_fma_f32 v253, v37, v121, v253
	v_cvt_pk_bf16_f32 v128, v188, v194
	v_cvt_pk_bf16_f32 v136, v249, v253
	ds_write_b32 v103, v128 offset:10240
	ds_write_b32 v103, v136 offset:18672
	v_fma_f32 v189, v150, v188, v189
	v_fma_f32 v195, v150, v194, v195
	v_fma_f32 v189, v16, v194, v189
	v_fma_f32 v195, v17, v188, v195
	v_fma_f32 v248, v152, v249, v248
	v_fma_f32 v252, v152, v253, v252
	v_fma_f32 v248, v36, v253, v248
	v_fma_f32 v252, v37, v249, v252
	v_cvt_pk_bf16_f32 v131, v189, v195
	v_cvt_pk_bf16_f32 v139, v248, v252
	ds_write_b32 v103, v131 offset:10512
	ds_write_b32 v103, v139 offset:18400
	v_fma_f32 v190, v150, v189, v190
	v_fma_f32 v196, v150, v195, v196
	v_fma_f32 v190, v16, v195, v190
	v_fma_f32 v196, v17, v189, v196
	v_fma_f32 v247, v152, v248, v247
	v_fma_f32 v251, v152, v252, v251
	v_fma_f32 v247, v36, v252, v247
	v_fma_f32 v251, v37, v248, v251
	v_cvt_pk_bf16_f32 v132, v190, v196
	v_cvt_pk_bf16_f32 v143, v247, v251
	ds_write_b32 v103, v132 offset:10784
	ds_write_b32 v103, v143 offset:18128
	v_fma_f32 v191, v150, v190, v191
	v_fma_f32 v197, v150, v196, v197
	v_fma_f32 v191, v16, v196, v191
	v_fma_f32 v197, v17, v190, v197
	v_fma_f32 v246, v152, v247, v246
	v_fma_f32 v250, v152, v251, v250
	v_fma_f32 v246, v36, v251, v246
	v_fma_f32 v250, v37, v247, v250
	v_cvt_pk_bf16_f32 v135, v191, v197
	v_cvt_pk_bf16_f32 v187, v246, v250
; #define LAS __attribute__((address_space(3)))
; __device__ __forceinline__ unsigned pk2(float lo, float hi) { f32x2 v = {lo, hi}; nbf2 r = __builtin_convertvector(v, nbf2); return __builtin_bit_cast(unsigned, r); }
; #define WAVE_LDS_FENCE() asm volatile("s_waitcnt lgkmcnt(0)" ::: "memory")
; __device__ __forceinline__ float bf_at(const u32x4& lo, const u32x4& hi, int r) { const unsigned w = (r < 8 ? lo : hi)[(r & 7) >> 1]; return (r & 1) ? bf_hi(w) : bf_lo(w); }
; __device__ __forceinline__ void s5_out_phase(LAS unsigned char* lds, const bf16_t* UZ, const unsigned char* ws, const float* dskip, bf16_t* YG) {
;     ...
; #pragma unroll
;             for (int rr = 0; rr < 16; ++rr) {
;                 const int r = rr, rb = 15 - rr;
;                 { const f32x2 bb = {bf_at(fre0, fre1, r), bf_at(fim0, fim1, r)};
;                   const f32x2 n2 = cmac((f32x2){xfr, xfi}, (f32x2){ap[0].x, ap[0].x}, (f32x2){-ap[0].y, ap[0].y}, bb); xfr = n2.x; xfi = n2.y;
;                   *(LAS unsigned*)(xf + r * XB_PITCH + lane * 4) = pk2(n2.x, n2.y); }
;                 { const f32x2 bb = {bf_at(bre0, bre1, rb), bf_at(bim0, bim1, rb)};
;                   const f32x2 n2 = cmac((f32x2){xbr, xbi}, (f32x2){ap[1].x, ap[1].x}, (f32x2){-ap[1].y, ap[1].y}, bb); xbr = n2.x; xbi = n2.y;
;                   *(LAS unsigned*)(xbk + rb * XB_PITCH + lane * 4) = pk2(n2.x, n2.y); }
;             }
;             WAVE_LDS_FENCE();
; #pragma unroll
;             for (int ks = 0; ks < 4; ++ks) {
;                 const bf16x8 Xf = *(const LAS bf16x8*)(xf + fr * XB_PITCH + (8 * fq + 32 * ks) * 2);
;                 const bf16x8 Xb = *(const LAS bf16x8*)(xbk + fr * XB_PITCH + (8 * fq + 32 * ks) * 2);
;                 accY[mf] = __builtin_amdgcn_mfma_f32_16x16x32_bf16(Cf[0][ks], Xf, accY[mf], 0, 0, 0);
;                 accY[mb] = __builtin_amdgcn_mfma_f32_16x16x32_bf16(Cf[1][ks], Xb, accY[mb], 0, 0, 0);
;             }
	ds_write_b32 v103, v135 offset:11056
	ds_write_b32 v103, v187 offset:17856
	v_fma_f32 v198, v150, v191, v198
	v_fma_f32 v202, v150, v197, v202
	v_fma_f32 v198, v16, v197, v198
	v_fma_f32 v202, v17, v191, v202
	v_fma_f32 v241, v152, v246, v241
	v_fma_f32 v245, v152, v250, v245
	v_fma_f32 v241, v36, v250, v241
	v_fma_f32 v245, v37, v246, v245
	v_cvt_pk_bf16_f32 v128, v198, v202
	v_cvt_pk_bf16_f32 v136, v241, v245
	ds_write_b32 v103, v128 offset:11328
	ds_write_b32 v103, v136 offset:17584
	v_fma_f32 v199, v150, v198, v199
	v_fma_f32 v203, v150, v202, v203
	v_fma_f32 v199, v16, v202, v199
	v_fma_f32 v203, v17, v198, v203
	v_fma_f32 v240, v152, v241, v240
	v_fma_f32 v244, v152, v245, v244
	v_fma_f32 v240, v36, v245, v240
	v_fma_f32 v244, v37, v241, v244
	v_cvt_pk_bf16_f32 v131, v199, v203
	v_cvt_pk_bf16_f32 v139, v240, v244
	ds_write_b32 v103, v131 offset:11600
	ds_write_b32 v103, v139 offset:17312
	v_fma_f32 v200, v150, v199, v200
	v_fma_f32 v204, v150, v203, v204
	v_fma_f32 v200, v16, v203, v200
	v_fma_f32 v204, v17, v199, v204
	v_fma_f32 v239, v152, v240, v239
	v_fma_f32 v243, v152, v244, v243
	v_fma_f32 v239, v36, v244, v239
	v_fma_f32 v243, v37, v240, v243
	v_cvt_pk_bf16_f32 v132, v200, v204
	v_cvt_pk_bf16_f32 v143, v239, v243
	ds_write_b32 v103, v132 offset:11872
	ds_write_b32 v103, v143 offset:17040
	v_fma_f32 v201, v150, v200, v201
	v_fma_f32 v205, v150, v204, v205
	v_fma_f32 v201, v16, v204, v201
	v_fma_f32 v205, v17, v200, v205
	v_fma_f32 v238, v152, v239, v238
	v_fma_f32 v242, v152, v243, v242
	v_fma_f32 v238, v36, v243, v238
	v_fma_f32 v242, v37, v239, v242
	v_cvt_pk_bf16_f32 v135, v201, v205
	v_cvt_pk_bf16_f32 v187, v238, v242
	ds_write_b32 v103, v135 offset:12144
	ds_write_b32 v103, v187 offset:16768
	v_fma_f32 v206, v150, v201, v206
	v_fma_f32 v210, v150, v205, v210
	v_fma_f32 v206, v16, v205, v206
	v_fma_f32 v210, v17, v201, v210
	v_fma_f32 v233, v152, v238, v233
	v_fma_f32 v237, v152, v242, v237
	v_fma_f32 v233, v36, v242, v233
	v_fma_f32 v237, v37, v238, v237
	v_cvt_pk_bf16_f32 v128, v206, v210
	v_cvt_pk_bf16_f32 v136, v233, v237
	ds_write_b32 v103, v128 offset:12416
	ds_write_b32 v103, v136 offset:16496
	v_fma_f32 v207, v150, v206, v207
	v_fma_f32 v211, v150, v210, v211
	v_fma_f32 v207, v16, v210, v207
	v_fma_f32 v211, v17, v206, v211
	v_fma_f32 v232, v152, v233, v232
	v_fma_f32 v236, v152, v237, v236
	v_fma_f32 v232, v36, v237, v232
	v_fma_f32 v236, v37, v233, v236
	v_cvt_pk_bf16_f32 v131, v207, v211
	v_cvt_pk_bf16_f32 v139, v232, v236
	ds_write_b32 v103, v131 offset:12688
	ds_write_b32 v103, v139 offset:16224
	v_fma_f32 v208, v150, v207, v208
	v_fma_f32 v212, v150, v211, v212
	v_fma_f32 v208, v16, v211, v208
	v_fma_f32 v212, v17, v207, v212
	v_fma_f32 v231, v152, v232, v231
	v_fma_f32 v235, v152, v236, v235
	v_fma_f32 v231, v36, v236, v231
	v_fma_f32 v235, v37, v232, v235
	v_cvt_pk_bf16_f32 v132, v208, v212
	v_cvt_pk_bf16_f32 v143, v231, v235
	ds_write_b32 v103, v132 offset:12960
	ds_write_b32 v103, v143 offset:15952
	v_fma_f32 v209, v150, v208, v209
	v_fma_f32 v213, v150, v212, v213
	v_fma_f32 v209, v16, v212, v209
	v_fma_f32 v213, v17, v208, v213
	v_fma_f32 v230, v152, v231, v230
	v_fma_f32 v234, v152, v235, v234
	v_fma_f32 v230, v36, v235, v230
	v_fma_f32 v234, v37, v231, v234
	v_cvt_pk_bf16_f32 v135, v209, v213
	v_cvt_pk_bf16_f32 v187, v230, v234
	ds_write_b32 v103, v135 offset:13232
	ds_write_b32 v103, v187 offset:15680
	v_fma_f32 v214, v150, v209, v214
	v_fma_f32 v218, v150, v213, v218
	v_fma_f32 v214, v16, v213, v214
	v_fma_f32 v218, v17, v209, v218
	v_fma_f32 v225, v152, v230, v225
	v_fma_f32 v229, v152, v234, v229
	v_fma_f32 v225, v36, v234, v225
	v_fma_f32 v229, v37, v230, v229
	v_cvt_pk_bf16_f32 v128, v214, v218
	v_cvt_pk_bf16_f32 v136, v225, v229
	ds_write_b32 v103, v128 offset:13504
	ds_write_b32 v103, v136 offset:15408
	v_fma_f32 v215, v150, v214, v215
	v_fma_f32 v219, v150, v218, v219
	v_fma_f32 v215, v16, v218, v215
	v_fma_f32 v219, v17, v214, v219
	v_fma_f32 v224, v152, v225, v224
	v_fma_f32 v228, v152, v229, v228
	v_fma_f32 v224, v36, v229, v224
	v_fma_f32 v228, v37, v225, v228
	v_cvt_pk_bf16_f32 v131, v215, v219
	v_cvt_pk_bf16_f32 v139, v224, v228
	ds_write_b32 v103, v131 offset:13776
	ds_write_b32 v103, v139 offset:15136
	v_fma_f32 v216, v150, v215, v216
	v_fma_f32 v220, v150, v219, v220
	v_fma_f32 v216, v16, v219, v216
	v_fma_f32 v220, v17, v215, v220
	v_fma_f32 v223, v152, v224, v223
	v_fma_f32 v227, v152, v228, v227
	v_fma_f32 v223, v36, v228, v223
	v_fma_f32 v227, v37, v224, v227
	v_cvt_pk_bf16_f32 v132, v216, v220
	v_cvt_pk_bf16_f32 v143, v223, v227
	ds_write_b32 v103, v132 offset:14048
	ds_write_b32 v103, v143 offset:14864
	v_fma_f32 v217, v150, v216, v217
	v_fma_f32 v221, v150, v220, v221
	v_fma_f32 v217, v16, v220, v217
	v_fma_f32 v221, v17, v216, v221
	v_fma_f32 v222, v152, v223, v222
	v_fma_f32 v226, v152, v227, v226
	v_fma_f32 v222, v36, v227, v222
	v_fma_f32 v226, v37, v223, v226
	v_cvt_pk_bf16_f32 v135, v217, v221
	v_cvt_pk_bf16_f32 v187, v222, v226
	ds_write_b32 v103, v135 offset:14320
	ds_write_b32 v103, v187 offset:14592
	v_mov_b32_e32 v114, v217
	v_mov_b32_e32 v119, v221
	v_mov_b32_e32 v121, v222
	v_mov_b32_e32 v127, v226
	ds_read_b128 v[188:191], v110 offset:10240
	ds_read_b128 v[194:197], v110 offset:10304
	ds_read_b128 v[198:201], v110 offset:10368
	ds_read_b128 v[202:205], v110 offset:10432
	ds_read_b128 v[206:209], v110 offset:14592
	ds_read_b128 v[210:213], v110 offset:14656
	ds_read_b128 v[214:217], v110 offset:14720
	ds_read_b128 v[218:221], v110 offset:14784
	s_waitcnt lgkmcnt(7)
	v_mfma_f32_16x16x32_bf16 v[44:47], v[0:3], v[188:191], v[44:47]
	s_waitcnt lgkmcnt(3)
; #define LAS __attribute__((address_space(3)))
; __device__ __forceinline__ unsigned pk2(float lo, float hi) { f32x2 v = {lo, hi}; nbf2 r = __builtin_convertvector(v, nbf2); return __builtin_bit_cast(unsigned, r); }
; __device__ __forceinline__ float bf_lo(unsigned w) { return __uint_as_float(w << 16); }
; __device__ __forceinline__ float bf_hi(unsigned w) { return __uint_as_float(w & 0xffff0000u); }
; __device__ __forceinline__ void s5_out_phase(LAS unsigned char* lds, const bf16_t* UZ, const unsigned char* ws, const float* dskip, bf16_t* YG) {
;     ...
; #pragma unroll
;             for (int ks = 0; ks < 4; ++ks) {
;                 const bf16x8 Xf = *(const LAS bf16x8*)(xf + fr * XB_PITCH + (8 * fq + 32 * ks) * 2);
;                 const bf16x8 Xb = *(const LAS bf16x8*)(xbk + fr * XB_PITCH + (8 * fq + 32 * ks) * 2);
;                 accY[mf] = __builtin_amdgcn_mfma_f32_16x16x32_bf16(Cf[0][ks], Xf, accY[mf], 0, 0, 0);
;                 accY[mb] = __builtin_amdgcn_mfma_f32_16x16x32_bf16(Cf[1][ks], Xb, accY[mb], 0, 0, 0);
;             }
;         }
; #pragma unroll
;         for (int m = 0; m < 4; ++m) {
;             const unsigned u0 = (unsigned)(unsigned short)Uf[m][0] | ((unsigned)(unsigned short)Uf[m][1] << 16), u1 = (unsigned)(unsigned short)Uf[m][2] | ((unsigned)(unsigned short)Uf[m][3] << 16);
;             const float y0 = gelu_f(accY[m][0] + dsk[0] * bf_lo(u0)), y1 = gelu_f(accY[m][1] + dsk[1] * bf_hi(u0));
;             const float y2 = gelu_f(accY[m][2] + dsk[2] * bf_lo(u1)), y3 = gelu_f(accY[m][3] + dsk[3] * bf_hi(u1));
;             u32x2 w; w.x = pk2(y0, y1); w.y = pk2(y2, y3);
;             *(u32x2*)(YG + (size_t)(rowbase + 16 * m + fr) * D + 16 * g + 4 * fq) = w;
;         }
	v_mfma_f32_16x16x32_bf16 v[48:51], v[20:23], v[206:209], v[48:51]
	v_mfma_f32_16x16x32_bf16 v[44:47], v[4:7], v[194:197], v[44:47]
	s_waitcnt lgkmcnt(2)
	v_mfma_f32_16x16x32_bf16 v[48:51], v[24:27], v[210:213], v[48:51]
	v_mfma_f32_16x16x32_bf16 v[44:47], v[8:11], v[198:201], v[44:47]
	s_waitcnt lgkmcnt(1)
	v_mfma_f32_16x16x32_bf16 v[48:51], v[28:31], v[214:217], v[48:51]
	v_mfma_f32_16x16x32_bf16 v[44:47], v[12:15], v[202:205], v[44:47]
	s_waitcnt lgkmcnt(0)
	v_mfma_f32_16x16x32_bf16 v[48:51], v[32:35], v[218:221], v[48:51]
	v_ashrrev_i32_e32 v167, 31, v166
	s_nop 7
	s_nop 4
	v_lshlrev_b32_e32 v188, 16, v172
	v_and_b32_e32 v189, 0xffff0000, v172
	s_waitcnt vmcnt(0)
	v_pk_fma_f32 v[188:189], v[40:41], v[188:189], v[48:49]
	v_lshlrev_b32_e32 v172, 16, v173
	v_fma_f32 v48, |v188|, s21, 1.0
	v_rcp_f32_e32 v190, v48
	v_fma_f32 v48, |v189|, s21, 1.0
	v_rcp_f32_e32 v191, v48
	v_pk_mul_f32 v[194:195], v[188:189], v[188:189]
	v_and_b32_e32 v173, 0xffff0000, v173
	v_mul_f32_e32 v48, 0xbf38aa3b, v194
	v_exp_f32_e32 v194, v48
	v_mov_b64_e32 v[48:49], s[4:5]
	v_pk_fma_f32 v[196:197], v[190:191], s[2:3], v[48:49] op_sel_hi:[1,0,0]
	v_mul_f32_e32 v114, 0xbf38aa3b, v195
	v_pk_fma_f32 v[196:197], v[190:191], v[196:197], s[8:9] op_sel_hi:[1,1,0]
	v_exp_f32_e32 v195, v114
	v_pk_fma_f32 v[196:197], v[190:191], v[196:197], s[20:21] op_sel_hi:[1,1,0]
	v_pk_fma_f32 v[50:51], v[42:43], v[172:173], v[50:51]
	v_pk_fma_f32 v[196:197], v[190:191], v[196:197], s[22:23] op_sel_hi:[1,1,0]
	v_fma_f32 v121, |v50|, s21, 1.0
	v_pk_mul_f32 v[190:191], v[190:191], v[196:197]
	v_rcp_f32_e32 v172, v121
	v_fma_f32 v121, |v51|, s21, 1.0
	v_pk_mul_f32 v[190:191], v[194:195], v[190:191]
	v_rcp_f32_e32 v173, v121
	v_pk_mul_f32 v[194:195], v[188:189], v[190:191]
	v_pk_fma_f32 v[190:191], v[188:189], v[190:191], v[188:189] neg_lo:[1,0,0] neg_hi:[1,0,0]
	v_cmp_gt_f32_e32 vcc, 0, v189
	s_nop 1
	v_cndmask_b32_e32 v114, v191, v195, vcc
	v_cmp_gt_f32_e32 vcc, 0, v188
	v_pk_mul_f32 v[188:189], v[50:51], v[50:51]
	s_nop 0
	v_mul_f32_e32 v121, 0xbf38aa3b, v188
	v_cndmask_b32_e32 v119, v190, v194, vcc
	v_exp_f32_e32 v188, v121
	v_pk_fma_f32 v[190:191], v[172:173], s[2:3], v[48:49] op_sel_hi:[1,0,0]
	v_mul_f32_e32 v121, 0xbf38aa3b, v189
	v_pk_fma_f32 v[190:191], v[172:173], v[190:191], s[8:9] op_sel_hi:[1,1,0]
	v_exp_f32_e32 v189, v121
	v_pk_fma_f32 v[190:191], v[172:173], v[190:191], s[20:21] op_sel_hi:[1,1,0]
	v_cmp_gt_f32_e32 vcc, 0, v51
	v_pk_fma_f32 v[190:191], v[172:173], v[190:191], s[22:23] op_sel_hi:[1,1,0]
	s_nop 0
	v_pk_mul_f32 v[172:173], v[172:173], v[190:191]
	s_nop 0
	v_pk_mul_f32 v[172:173], v[188:189], v[172:173]
	s_nop 0
	v_pk_mul_f32 v[188:189], v[50:51], v[172:173]
	v_pk_fma_f32 v[172:173], v[50:51], v[172:173], v[50:51] neg_lo:[1,0,0] neg_hi:[1,0,0]
	s_nop 0
	v_cndmask_b32_e32 v51, v173, v189, vcc
	v_cmp_gt_f32_e32 vcc, 0, v50
	v_cvt_pk_bf16_f32 v50, v119, v114
	s_nop 0
	v_cndmask_b32_e32 v121, v172, v188, vcc
	v_lshlrev_b64 v[172:173], 11, v[166:167]
	v_cvt_pk_bf16_f32 v51, v121, v51
	v_lshl_add_u64 v[172:173], v[154:155], 0, v[172:173]
	global_store_dwordx2 v[172:173], v[50:51], off
	v_lshlrev_b32_e32 v50, 16, v170
	v_and_b32_e32 v51, 0xffff0000, v170
	v_pk_fma_f32 v[50:51], v[40:41], v[50:51], v[56:57]
	s_nop 0
	v_fma_f32 v56, |v50|, s21, 1.0
	v_fma_f32 v57, |v51|, s21, 1.0
	v_rcp_f32_e32 v56, v56
	v_rcp_f32_e32 v57, v57
	v_pk_mul_f32 v[172:173], v[50:51], v[50:51]
	v_cmp_gt_f32_e32 vcc, 0, v51
	v_mul_f32_e32 v114, 0xbf38aa3b, v172
	v_exp_f32_e32 v172, v114
	v_pk_fma_f32 v[188:189], v[56:57], s[2:3], v[48:49] op_sel_hi:[1,0,0]
	v_mul_f32_e32 v114, 0xbf38aa3b, v173
	v_pk_fma_f32 v[188:189], v[56:57], v[188:189], s[8:9] op_sel_hi:[1,1,0]
	v_exp_f32_e32 v173, v114
	v_pk_fma_f32 v[188:189], v[56:57], v[188:189], s[20:21] op_sel_hi:[1,1,0]
	s_nop 0
	v_pk_fma_f32 v[188:189], v[56:57], v[188:189], s[22:23] op_sel_hi:[1,1,0]
	s_nop 0
	v_pk_mul_f32 v[56:57], v[56:57], v[188:189]
	s_nop 0
	v_pk_mul_f32 v[56:57], v[172:173], v[56:57]
	s_nop 0
	v_pk_mul_f32 v[172:173], v[50:51], v[56:57]
	v_pk_fma_f32 v[56:57], v[50:51], v[56:57], v[50:51] neg_lo:[1,0,0] neg_hi:[1,0,0]
	v_and_b32_e32 v51, 0xffff0000, v171
	v_cndmask_b32_e32 v114, v57, v173, vcc
	v_cmp_gt_f32_e32 vcc, 0, v50
	v_lshlrev_b32_e32 v50, 16, v171
	v_pk_fma_f32 v[50:51], v[42:43], v[50:51], v[58:59]
	v_cndmask_b32_e32 v119, v56, v172, vcc
	v_fma_f32 v56, |v50|, s21, 1.0
	v_fma_f32 v57, |v51|, s21, 1.0
	v_rcp_f32_e32 v56, v56
	v_rcp_f32_e32 v57, v57
	v_pk_mul_f32 v[58:59], v[50:51], v[50:51]
	v_cmp_gt_f32_e32 vcc, 0, v51
	v_mul_f32_e32 v58, 0xbf38aa3b, v58
	v_pk_fma_f32 v[170:171], v[56:57], s[2:3], v[48:49] op_sel_hi:[1,0,0]
	v_mul_f32_e32 v59, 0xbf38aa3b, v59
	v_exp_f32_e32 v58, v58
	v_pk_fma_f32 v[170:171], v[56:57], v[170:171], s[8:9] op_sel_hi:[1,1,0]
	v_exp_f32_e32 v59, v59
	v_pk_fma_f32 v[170:171], v[56:57], v[170:171], s[20:21] op_sel_hi:[1,1,0]
	v_mov_b64_e32 v[172:173], v[174:175]
	v_pk_fma_f32 v[170:171], v[56:57], v[170:171], s[22:23] op_sel_hi:[1,1,0]
	s_nop 0
	v_pk_mul_f32 v[56:57], v[56:57], v[170:171]
	v_mov_b64_e32 v[170:171], v[176:177]
	v_pk_mul_f32 v[56:57], v[58:59], v[56:57]
	s_nop 0
	v_pk_mul_f32 v[58:59], v[50:51], v[56:57]
	v_pk_fma_f32 v[56:57], v[50:51], v[56:57], v[50:51] neg_lo:[1,0,0] neg_hi:[1,0,0]
	s_nop 0
	v_cndmask_b32_e32 v51, v57, v59, vcc
; __device__ __forceinline__ unsigned pk2(float lo, float hi) { f32x2 v = {lo, hi}; nbf2 r = __builtin_convertvector(v, nbf2); return __builtin_bit_cast(unsigned, r); }
; __device__ __forceinline__ float bf_lo(unsigned w) { return __uint_as_float(w << 16); }
; __device__ __forceinline__ float bf_hi(unsigned w) { return __uint_as_float(w & 0xffff0000u); }
; __device__ __forceinline__ void s5_out_phase(LAS unsigned char* lds, const bf16_t* UZ, const unsigned char* ws, const float* dskip, bf16_t* YG) {
;     ...
; #pragma unroll
;         for (int m = 0; m < 4; ++m) {
;             const unsigned u0 = (unsigned)(unsigned short)Uf[m][0] | ((unsigned)(unsigned short)Uf[m][1] << 16), u1 = (unsigned)(unsigned short)Uf[m][2] | ((unsigned)(unsigned short)Uf[m][3] << 16);
;             const float y0 = gelu_f(accY[m][0] + dsk[0] * bf_lo(u0)), y1 = gelu_f(accY[m][1] + dsk[1] * bf_hi(u0));
;             const float y2 = gelu_f(accY[m][2] + dsk[2] * bf_lo(u1)), y3 = gelu_f(accY[m][3] + dsk[3] * bf_hi(u1));
;             u32x2 w; w.x = pk2(y0, y1); w.y = pk2(y2, y3);
;             *(u32x2*)(YG + (size_t)(rowbase + 16 * m + fr) * D + 16 * g + 4 * fq) = w;
;         }
;     }
	v_cmp_gt_f32_e32 vcc, 0, v50
	v_cvt_pk_bf16_f32 v50, v119, v114
	s_nop 0
	v_cndmask_b32_e32 v56, v56, v58, vcc
	v_cvt_pk_bf16_f32 v51, v56, v51
	v_add_u32_e32 v56, 16, v166
	v_ashrrev_i32_e32 v57, 31, v56
	v_lshlrev_b64 v[56:57], 11, v[56:57]
	v_lshl_add_u64 v[56:57], v[154:155], 0, v[56:57]
	global_store_dwordx2 v[56:57], v[50:51], off
	v_lshlrev_b32_e32 v50, 16, v168
	v_and_b32_e32 v51, 0xffff0000, v168
	v_pk_fma_f32 v[50:51], v[40:41], v[50:51], v[52:53]
	s_nop 0
	v_fma_f32 v52, |v50|, s21, 1.0
	v_fma_f32 v53, |v51|, s21, 1.0
	v_rcp_f32_e32 v52, v52
	v_rcp_f32_e32 v53, v53
	v_pk_mul_f32 v[56:57], v[50:51], v[50:51]
	v_cmp_gt_f32_e32 vcc, 0, v51
	v_mul_f32_e32 v56, 0xbf38aa3b, v56
	v_pk_fma_f32 v[58:59], v[52:53], s[2:3], v[48:49] op_sel_hi:[1,0,0]
	v_mul_f32_e32 v57, 0xbf38aa3b, v57
	v_exp_f32_e32 v56, v56
	v_pk_fma_f32 v[58:59], v[52:53], v[58:59], s[8:9] op_sel_hi:[1,1,0]
	v_exp_f32_e32 v57, v57
	v_pk_fma_f32 v[58:59], v[52:53], v[58:59], s[20:21] op_sel_hi:[1,1,0]
	s_nop 0
	v_pk_fma_f32 v[58:59], v[52:53], v[58:59], s[22:23] op_sel_hi:[1,1,0]
	s_nop 0
	v_pk_mul_f32 v[52:53], v[52:53], v[58:59]
	s_nop 0
	v_pk_mul_f32 v[52:53], v[56:57], v[52:53]
	s_nop 0
	v_pk_mul_f32 v[56:57], v[50:51], v[52:53]
	v_pk_fma_f32 v[52:53], v[50:51], v[52:53], v[50:51] neg_lo:[1,0,0] neg_hi:[1,0,0]
	v_and_b32_e32 v51, 0xffff0000, v169
	v_cndmask_b32_e32 v58, v53, v57, vcc
	v_cmp_gt_f32_e32 vcc, 0, v50
	v_lshlrev_b32_e32 v50, 16, v169
	v_pk_fma_f32 v[50:51], v[42:43], v[50:51], v[54:55]
	v_cndmask_b32_e32 v59, v52, v56, vcc
	v_fma_f32 v52, |v50|, s21, 1.0
	v_fma_f32 v53, |v51|, s21, 1.0
	v_rcp_f32_e32 v52, v52
	v_rcp_f32_e32 v53, v53
	v_pk_mul_f32 v[54:55], v[50:51], v[50:51]
	v_cmp_gt_f32_e32 vcc, 0, v51
	v_mul_f32_e32 v54, 0xbf38aa3b, v54
	v_pk_fma_f32 v[56:57], v[52:53], s[2:3], v[48:49] op_sel_hi:[1,0,0]
	v_mul_f32_e32 v55, 0xbf38aa3b, v55
	v_exp_f32_e32 v54, v54
	v_pk_fma_f32 v[56:57], v[52:53], v[56:57], s[8:9] op_sel_hi:[1,1,0]
	v_exp_f32_e32 v55, v55
	v_pk_fma_f32 v[56:57], v[52:53], v[56:57], s[20:21] op_sel_hi:[1,1,0]
	v_mov_b64_e32 v[168:169], v[178:179]
	v_pk_fma_f32 v[56:57], v[52:53], v[56:57], s[22:23] op_sel_hi:[1,1,0]
	s_nop 0
	v_pk_mul_f32 v[52:53], v[52:53], v[56:57]
	s_nop 0
	v_pk_mul_f32 v[52:53], v[54:55], v[52:53]
	s_nop 0
	v_pk_mul_f32 v[54:55], v[50:51], v[52:53]
	v_pk_fma_f32 v[52:53], v[50:51], v[52:53], v[50:51] neg_lo:[1,0,0] neg_hi:[1,0,0]
	s_nop 0
	v_cndmask_b32_e32 v51, v53, v55, vcc
	v_cmp_gt_f32_e32 vcc, 0, v50
	v_cvt_pk_bf16_f32 v50, v59, v58
	s_nop 0
	v_cndmask_b32_e32 v52, v52, v54, vcc
	v_cvt_pk_bf16_f32 v51, v52, v51
	v_add_u32_e32 v52, 32, v166
	v_ashrrev_i32_e32 v53, 31, v52
	v_lshlrev_b64 v[52:53], 11, v[52:53]
	v_lshl_add_u64 v[52:53], v[154:155], 0, v[52:53]
	global_store_dwordx2 v[52:53], v[50:51], off
	v_lshlrev_b32_e32 v50, 16, v116
	v_and_b32_e32 v51, 0xffff0000, v116
	v_pk_fma_f32 v[44:45], v[40:41], v[50:51], v[44:45]
	s_nop 0
	v_fma_f32 v50, |v44|, s21, 1.0
	v_fma_f32 v51, |v45|, s21, 1.0
	v_rcp_f32_e32 v50, v50
	v_rcp_f32_e32 v51, v51
	v_pk_mul_f32 v[52:53], v[44:45], v[44:45]
	v_cmp_gt_f32_e32 vcc, 0, v45
	v_mul_f32_e32 v52, 0xbf38aa3b, v52
	v_pk_fma_f32 v[54:55], v[50:51], s[2:3], v[48:49] op_sel_hi:[1,0,0]
	v_mul_f32_e32 v53, 0xbf38aa3b, v53
	v_exp_f32_e32 v52, v52
	v_pk_fma_f32 v[54:55], v[50:51], v[54:55], s[8:9] op_sel_hi:[1,1,0]
	v_exp_f32_e32 v53, v53
	v_pk_fma_f32 v[54:55], v[50:51], v[54:55], s[20:21] op_sel_hi:[1,1,0]
	s_nop 0
	v_pk_fma_f32 v[54:55], v[50:51], v[54:55], s[22:23] op_sel_hi:[1,1,0]
	s_nop 0
	v_pk_mul_f32 v[50:51], v[50:51], v[54:55]
	s_nop 0
	v_pk_mul_f32 v[50:51], v[52:53], v[50:51]
	s_nop 0
	v_pk_mul_f32 v[52:53], v[44:45], v[50:51]
	v_pk_fma_f32 v[50:51], v[44:45], v[50:51], v[44:45] neg_lo:[1,0,0] neg_hi:[1,0,0]
	v_and_b32_e32 v45, 0xffff0000, v117
	v_cndmask_b32_e32 v53, v51, v53, vcc
	v_cmp_gt_f32_e32 vcc, 0, v44
	v_lshlrev_b32_e32 v44, 16, v117
	v_pk_fma_f32 v[44:45], v[42:43], v[44:45], v[46:47]
	v_cndmask_b32_e32 v52, v50, v52, vcc
	v_fma_f32 v46, |v44|, s21, 1.0
	v_fma_f32 v47, |v45|, s21, 1.0
	v_rcp_f32_e32 v46, v46
	v_rcp_f32_e32 v47, v47
	v_pk_mul_f32 v[50:51], v[44:45], v[44:45]
	v_cmp_gt_f32_e32 vcc, 0, v45
	v_mul_f32_e32 v50, 0xbf38aa3b, v50
	v_pk_fma_f32 v[48:49], v[46:47], s[2:3], v[48:49] op_sel_hi:[1,0,0]
	v_mul_f32_e32 v51, 0xbf38aa3b, v51
	v_exp_f32_e32 v50, v50
	v_pk_fma_f32 v[48:49], v[46:47], v[48:49], s[8:9] op_sel_hi:[1,1,0]
	v_exp_f32_e32 v51, v51
	v_pk_fma_f32 v[48:49], v[46:47], v[48:49], s[20:21] op_sel_hi:[1,1,0]
	v_mov_b64_e32 v[116:117], v[180:181]
	v_pk_fma_f32 v[48:49], v[46:47], v[48:49], s[22:23] op_sel_hi:[1,1,0]
	s_nop 0
	v_pk_mul_f32 v[46:47], v[46:47], v[48:49]
	s_nop 0
	v_pk_mul_f32 v[46:47], v[50:51], v[46:47]
	s_nop 0
	v_pk_mul_f32 v[48:49], v[44:45], v[46:47]
	v_pk_fma_f32 v[46:47], v[44:45], v[46:47], v[44:45] neg_lo:[1,0,0] neg_hi:[1,0,0]
	s_nop 0
	v_cndmask_b32_e32 v45, v47, v49, vcc
	v_cmp_gt_f32_e32 vcc, 0, v44
	v_cvt_pk_bf16_f32 v44, v52, v53
	s_nop 0
	v_cndmask_b32_e32 v46, v46, v48, vcc
	v_cvt_pk_bf16_f32 v45, v46, v45
	v_add_u32_e32 v46, 48, v166
	v_ashrrev_i32_e32 v47, 31, v46
	v_lshlrev_b64 v[46:47], 11, v[46:47]
	v_lshl_add_u64 v[46:47], v[154:155], 0, v[46:47]
	v_add_u32_e32 v166, s3, v166
	s_andn2_b64 vcc, exec, s[24:25]
	global_store_dwordx2 v[46:47], v[44:45], off
	s_cbranch_vccz .LBB0_762
